# hand-written RWKV scan phase: lean 8-wave prep (MFMA lora + packed f32) with padded LDS tables, next-chunk loads issued outside prep (scanners at group boundaries, idle waves after barrier)
# speedup vs baseline: 1.0358x; 1.0089x over previous
;     __device__ __forceinline__ bf16* R(int i) const { return (bf16*)(ws + OFF_R0 + (size_t)i * RSZ); }
; __device__ __forceinline__ void phase_rwkv_scan(const Fr& F, int jr) {
;     ...
;     const int bxs = (int)blockIdx.x, bxcd = (gridDim.x == 256) ? (bxs & 7) * 32 + (bxs >> 3) : bxs;
;     for (int task = bxcd; task < 256; task += gridDim.x) {
;         const int half = task & 1, h = (task >> 1) & 15, b = (task >> 5) & 3, s = task >> 7;
;         bf16* Yb = F.R(s);
;         const float* w0 = F.a->in[9] + (size_t)(jr * 2 + s) * D + h * 64; const float* a0 = F.a->in[12] + (size_t)(jr * 2 + s) * D + h * 64;
;         const float* kkw = F.a->in[15] + (size_t)jr * D + h * 64; const float* kaw = F.a->in[16] + (size_t)jr * D + h * 64;
;         f32x2 S01 = {0.f, 0.f}, S23 = {0.f, 0.f};
;         const int ks = 4 * l15, rloc = 4 * wave + lq;
;         const int pt = wave & 3, ht0 = (wave >> 2) * 2;
;         const int p1 = pt * 16 + l15;
;         const int p2 = tid >> 3, j8 = tid & 7, hk0 = 8 * j8;
;         bf16x8 Bw[2][2], Ba[2][2]; float w0v[2], a0v[2];
; #pragma unroll
;         for (int hh = 0; hh < 2; ++hh) { const int hk = (ht0 + hh) * 16 + l15, e = h * 64 + hk; w0v[hh] = w0[hk]; a0v[hh] = a0[hk];
; #pragma unroll
;             for (int kst = 0; kst < 2; ++kst) { Bw[hh][kst] = *(const bf16x8*)(L2T + ((size_t)s * D + e) * 64 + 32 * kst + 8 * lq); Ba[hh][kst] = *(const bf16x8*)(L2T + ((size_t)(2 + s) * D + e) * 64 + 32 * kst + 8 * lq); } }
;         float kkc[8], kac[8], rkc[8];
; #pragma unroll
;         for (int i = 0; i < 8; ++i) { kkc[i] = kkw[hk0 + i]; kac[i] = kaw[hk0 + i]; rkc[i] = F.a->in[17][(size_t)jr * D + h * 64 + hk0 + i]; }
;         float* Bon = (float*)(F.ws + OFF_R0 + 6 * RSZ + 16 * MiB);
;         bf16x8 Aw[2], Aa[2]; u32x4 kw, rw; u32x2 vw;
;         {   const size_t row1 = (size_t)b * TB + tokof(s, p1), row2 = (size_t)b * TB + tokof(s, p2);
; #pragma unroll
;             for (int kst = 0; kst < 2; ++kst) { Aw[kst] = *(const bf16x8*)(LM + row1 * 256 + 64 * s + 32 * kst + 8 * lq); Aa[kst] = *(const bf16x8*)(LM + row1 * 256 + 128 + 64 * s + 32 * kst + 8 * lq); }
;             kw = *(const u32x4*)(Kb + row2 * D + h * 64 + hk0); rw = *(const u32x4*)(Rb + row2 * D + h * 64 + hk0); vw = *(const u32x2*)(Vb + row2 * D + h * 64 + 32 * half + 4 * j8); }
.LBB0_552:
	s_or_b64 exec, exec, s[6:7]
	v_cmp_gt_i32_e32 vcc, 6, v1
	v_cmp_lt_i32_e64 s[6:7], 5, v2
	s_and_b64 s[6:7], vcc, s[6:7]
	s_and_saveexec_b64 s[12:13], s[6:7]
	s_cbranch_execz .LBB0_565
	s_and_b32 s3, s2, 7
	s_lshl_b32 s3, s3, 5
	s_lshr_b32 s6, s2, 3
	s_add_i32 s3, s3, s6
	s_lshr_b32 s6, s3, 7
	s_bfe_u32 s7, s3, 0x20005
	s_bfe_u32 s8, s3, 0x40001
	s_and_b32 s9, s3, 1
	s_cmp_gt_u32 s68, 3
	s_cbranch_scc1 .Lrw0_nosc
	v_mov_b32_e32 v236, 0
	v_mov_b32_e32 v237, 0
	v_mov_b32_e32 v238, 0
	v_mov_b32_e32 v239, 0
	v_mov_b32_e32 v240, 0
	v_mov_b32_e32 v241, 0
	v_mov_b32_e32 v242, 0
	v_mov_b32_e32 v243, 0
	v_and_b32_e32 v197, 15, v130
	v_lshlrev_b32_e32 v244, 4, v197
	v_add_u32_e32 v245, 0x11000, v244
	v_lshrrev_b32_e32 v198, 4, v130
	v_lshrrev_b32_e32 v199, 3, v197
	v_lshl_add_u32 v199, v198, 1, v199
	s_lshl_b32 s91, s68, 3
	v_add_u32_e32 v199, s91, v199
	v_lshlrev_b32_e32 v199, 3, v199
	v_add_u32_e32 v246, 0x15400, v199
	s_mul_i32 s91, s68, 0x2400
	s_add_i32 s91, s91, 0x19800
	s_cmp_eq_u32 s68, 3
	s_cselect_b32 s91, 0x20800, s91
	v_mul_u32_u24_e32 v248, 0x90, v130
	v_add_u32_e32 v248, s91, v248
	v_mul_u32_u24_e32 v198, 0x90, v198
	v_lshl_add_u32 v198, v197, 3, v198
	v_add_u32_e32 v247, s91, v198
	v_lshrrev_b32_e32 v249, 2, v130
	s_cmp_eq_u32 s6, 0
	s_cbranch_scc1 .Lrw0_sdir0
	v_sub_u32_e32 v249, 0, v249
.Lrw0_sdir0:
	v_and_b32_e32 v197, 3, v130
	s_lshl_b32 s91, s68, 4
	v_lshl_add_u32 v250, v197, 2, s91
	s_mul_i32 s91, s6, 0x2200000
	s_add_u32 s88, s26, s91
	s_addc_u32 s89, s27, 0
	s_add_u32 s88, s88, 0x1200000
	s_addc_u32 s89, s89, 0
	s_mul_i32 s91, s7, 0x880000
	s_add_u32 s88, s88, s91
	s_addc_u32 s89, s89, 0
	s_and_b32 s91, s3, 31
	s_lshl_b32 s91, s91, 6
	s_add_u32 s88, s88, s91
	s_addc_u32 s89, s89, 0
.Lrw0_nosc:
	v_mov_b32_e32 v122, 0xbfb8aa3b
	v_mov_b32_e32 v123, 0xbfb8aa3b
	v_mov_b32_e32 v124, 0xbf1b4598
	v_mov_b32_e32 v125, 0xbf1b4598
	v_mov_b32_e32 v126, 0x3fb8aa3b
	v_mov_b32_e32 v127, 0x3fb8aa3b
	s_and_b32 s14, s68, 3
	s_lshr_b32 s15, s68, 2
	v_and_b32_e32 v196, 15, v130
	v_lshrrev_b32_e32 v217, 4, v130
	s_lshl_b32 s17, s14, 4
	v_add_u32_e32 v216, s17, v196
	v_mov_b32_e32 v218, v216
	s_cmp_eq_u32 s6, 0
	s_cbranch_scc1 .Lrw0_hdir0
	v_sub_u32_e32 v218, 0, v216
.Lrw0_hdir0:
	s_mul_i32 s16, s7, 0x1100
	v_lshlrev_b32_e32 v221, 4, v217
	s_lshl_b32 s17, s15, 6
	v_lshl_add_u32 v219, v217, 3, s17
	s_xor_b32 s18, s17, 64
	v_lshl_add_u32 v220, v217, 3, s18
	s_lshl_b32 s17, s15, 7
	v_mul_u32_u24_e32 v197, 0x110, v216
	v_add_u32_e32 v197, s17, v197
	v_lshl_add_u32 v222, v217, 4, v197
	v_add_u32_e32 v224, 0x11000, v222
	v_lshl_add_u32 v223, v217, 5, v197
	v_add_u32_e32 v223, 0x15400, v223
	s_lshl_b32 s17, s6, 7
	s_add_u32 s20, s26, 0xde00000
	s_addc_u32 s21, s27, 0
	s_add_u32 s20, s20, s17
	s_addc_u32 s21, s21, 0
	s_lshl_b32 s17, s8, 7
	s_add_u32 s22, s26, 0xbc00000
	s_addc_u32 s23, s27, 0
	s_add_u32 s22, s22, s17
	s_addc_u32 s23, s23, 0
	s_add_u32 s24, s26, 0x9a00000
	s_addc_u32 s25, s27, 0
	s_add_u32 s24, s24, s17
	s_addc_u32 s25, s25, 0
	s_lshl_b32 s18, s9, 6
	s_add_i32 s17, s17, s18
	s_lshl_b32 s18, s15, 5
	s_add_i32 s17, s17, s18
	s_add_u32 s42, s26, 0x5600000
	s_addc_u32 s43, s27, 0
	s_add_u32 s42, s42, s17
	s_addc_u32 s43, s43, 0
	s_lshl_b32 s17, s8, 2
	s_add_u32 s44, s26, 0xee00000
	s_addc_u32 s45, s27, 0
	s_add_u32 s44, s44, s17
	s_addc_u32 s45, s45, 0
	s_or_b32 s17, s9, s15
	s_cmp_eq_u32 s17, 0
	s_cselect_b32 s32, 1, 0
	s_load_dwordx2 s[46:47], s[0:1], 0x48
	s_load_dwordx2 s[48:49], s[0:1], 0x60
	s_load_dwordx2 s[50:51], s[0:1], 0x78
	s_load_dwordx2 s[52:53], s[0:1], 0x80
	s_load_dwordx2 s[54:55], s[0:1], 0x88
	s_lshl_b32 s17, s8, 8
	s_lshl_b32 s18, s15, 7
	s_add_i32 s19, s17, s18
	v_lshl_add_u32 v198, v217, 4, s19
	s_xor_b32 s18, s18, 128
	s_add_i32 s19, s17, s18
	v_lshl_add_u32 v199, v217, 4, s19
	s_waitcnt lgkmcnt(0)
	s_lshl_b32 s17, s6, 12
	s_add_u32 s46, s46, s17
	s_addc_u32 s47, s47, 0
	s_add_u32 s48, s48, s17
	s_addc_u32 s49, s49, 0
	global_load_dwordx4 v[32:35], v198, s[46:47] offset:0
	global_load_dwordx4 v[40:43], v198, s[48:49] offset:0
	global_load_dwordx4 v[64:67], v198, s[52:53] offset:0
	global_load_dwordx4 v[36:39], v198, s[46:47] offset:64
	global_load_dwordx4 v[44:47], v198, s[48:49] offset:64
	global_load_dwordx4 v[68:71], v198, s[52:53] offset:64
	global_load_dwordx4 v[48:51], v198, s[50:51] offset:0
	global_load_dwordx4 v[72:75], v198, s[54:55] offset:0
	global_load_dwordx4 v[52:55], v198, s[50:51] offset:64
	global_load_dwordx4 v[76:79], v198, s[54:55] offset:64
	global_load_dwordx4 v[56:59], v199, s[50:51] offset:0
	global_load_dwordx4 v[80:83], v199, s[54:55] offset:0
	global_load_dwordx4 v[60:63], v199, s[50:51] offset:64
	global_load_dwordx4 v[84:87], v199, s[54:55] offset:64
	s_lshl_b32 s17, s8, 6
	s_lshl_b32 s18, s15, 5
	s_add_i32 s17, s17, s18
	v_add_u32_e32 v200, s17, v196
	v_lshlrev_b32_e32 v200, 7, v200
	v_add_u32_e32 v200, v200, v221
	s_lshl_b32 s17, s6, 17
	s_add_u32 s46, s26, 0x200000
	s_addc_u32 s47, s27, 0
	s_add_u32 s46, s46, s17
	s_addc_u32 s47, s47, 0
	s_add_u32 s48, s46, 0x40000
	s_addc_u32 s49, s47, 0
	global_load_dwordx4 v[0:3], v200, s[46:47] offset:0
	global_load_dwordx4 v[16:19], v200, s[48:49] offset:0
	global_load_dwordx4 v[4:7], v200, s[46:47] offset:64
	global_load_dwordx4 v[20:23], v200, s[48:49] offset:64
	global_load_dwordx4 v[8:11], v200, s[46:47] offset:2048
	global_load_dwordx4 v[24:27], v200, s[48:49] offset:2048
	global_load_dwordx4 v[12:15], v200, s[46:47] offset:2112
	global_load_dwordx4 v[28:31], v200, s[48:49] offset:2112
	s_mov_b32 s10, 0
	s_lshl_b32 s17, s10, 6
	s_cmp_lt_u32 s10, 4
	s_movk_i32 s18, 0x11ff
	s_cselect_b32 s18, 0xff, s18
	s_sub_i32 s18, s18, s17
	s_cmp_eq_u32 s6, 0
	s_cselect_b32 s17, s17, s18
	s_add_i32 s17, s17, s16
	v_add_u32_e32 v231, s17, v218
	v_lshl_add_u32 v226, v231, 9, v221
	v_lshl_add_u32 v227, v231, 11, v219
	v_lshl_add_u32 v228, v231, 11, v220
	v_lshlrev_b32_e32 v229, 3, v217
	v_lshl_add_u32 v229, v231, 11, v229
	v_lshlrev_b32_e32 v230, 6, v231
	global_load_dwordx4 v[88:91], v226, s[20:21]
	global_load_dwordx4 v[92:95], v226, s[20:21] offset:64
	global_load_dwordx4 v[96:99], v226, s[20:21] offset:256
	global_load_dwordx4 v[100:103], v226, s[20:21] offset:320
	global_load_dwordx2 v[104:105], v227, s[22:23] offset:0
	global_load_dwordx2 v[106:107], v227, s[22:23] offset:32
	global_load_dwordx2 v[108:109], v228, s[22:23] offset:0
	global_load_dwordx2 v[110:111], v228, s[22:23] offset:32
	global_load_dwordx2 v[112:113], v227, s[24:25] offset:0
	global_load_dwordx2 v[114:115], v227, s[24:25] offset:32
	global_load_dwordx2 v[116:117], v228, s[24:25] offset:0
	global_load_dwordx2 v[118:119], v228, s[24:25] offset:32
	global_load_dwordx2 v[120:121], v229, s[42:43]
.Lrw0_chunk:
	s_and_b32 s17, s10, 1
	s_xor_b32 s17, s17, 1
	s_and_b32 s11, s32, s17
	v_mov_b32_e32 v225, v230
	s_cmp_eq_u32 s10, 0
	s_cbranch_scc1 .Lrw0_hwall0
	s_cmp_gt_u32 s68, 3
	s_cbranch_scc1 .Lrw0_hwall0
	s_waitcnt vmcnt(1)
	s_branch .Lrw0_hwdone0

; __device__ __forceinline__ float sigm(float x) { return __builtin_amdgcn_rcpf(1.f + __expf(-x)); }
; template <int CTRL> __device__ __forceinline__ float dppf(float x) { return __builtin_bit_cast(float, __builtin_amdgcn_update_dpp(0, __builtin_bit_cast(int, x), CTRL, 0xF, 0xF, false)); }
; #define LDS_BAR() asm volatile("s_waitcnt lgkmcnt(0)\n\ts_barrier" ::: "memory")
; __device__ __forceinline__ void phase_rwkv_scan(const Fr& F, int jr) {
;     ...
;                 for (int kst = 0; kst < 2; ++kst) { cw = __builtin_amdgcn_mfma_f32_16x16x32_bf16(Aw[kst], Bw[hh][kst], cw, 0, 0, 0); ca = __builtin_amdgcn_mfma_f32_16x16x32_bf16(Aa[kst], Ba[hh][kst], ca, 0, 0, 0); }
; #pragma unroll
;                 for (int reg = 0; reg < 4; ++reg) { const int pp = pt * 16 + lq * 4 + reg;
;                     Wv[pp * 64 + hk] = __expf(-0.60653066f * sigm(w0v[hh] + cw[reg]));
;                     Av[pp * 64 + hk] = sigm(a0v[hh] + ca[reg]); }
;             }
;             LDS_BAR();
;             {
;                 const float kr[8] = {lo_bf(kw.x), hi_bf(kw.x), lo_bf(kw.y), hi_bf(kw.y), lo_bf(kw.z), hi_bf(kw.z), lo_bf(kw.w), hi_bf(kw.w)};
;                 const float rr[8] = {lo_bf(rw.x), hi_bf(rw.x), lo_bf(rw.y), hi_bf(rw.y), lo_bf(rw.z), hi_bf(rw.z), lo_bf(rw.w), hi_bf(rw.w)};
;                 float kq[8]; float ss = 0.f, bon = 0.f;
; #pragma unroll
;                 for (int i = 0; i < 8; ++i) { kq[i] = kr[i] * kkc[i]; ss += kq[i] * kq[i]; bon += rr[i] * kr[i] * rkc[i]; }
;                 ss += dppf<0xB1>(ss); ss += dppf<0x4E>(ss); ss += dppf<0x141>(ss); bon += dppf<0xB1>(bon); bon += dppf<0x4E>(bon); bon += dppf<0x141>(bon);
;                 if (s == 0 && half == 0 && j8 == 0) Bon[((size_t)b * TB + tokof(s, chunk * 64 + p2)) * 16 + h] = bon;
;     ...
;                 const size_t row1 = (size_t)b * TB + tokof(s, (chunk + 1) * 64 + p1), row2 = (size_t)b * TB + tokof(s, (chunk + 1) * 64 + p2);
; #pragma unroll
;                 for (int kst = 0; kst < 2; ++kst) { Aw[kst] = *(const bf16x8*)(LM + row1 * 256 + 64 * s + 32 * kst + 8 * lq); Aa[kst] = *(const bf16x8*)(LM + row1 * 256 + 128 + 64 * s + 32 * kst + 8 * lq); }
;                 kw = *(const u32x4*)(Kb + row2 * D + h * 64 + hk0); rw = *(const u32x4*)(Rb + row2 * D + h * 64 + hk0); vw = *(const u32x2*)(Vb + row2 * D + h * 64 + 32 * half + 4 * j8);
.Lrw0_hwdone0:
	s_add_i32 s10, s10, 1
	s_min_u32 s19, s10, 67
	s_lshl_b32 s17, s19, 6
	s_cmp_lt_u32 s19, 4
	s_movk_i32 s18, 0x11ff
	s_cselect_b32 s18, 0xff, s18
	s_sub_i32 s18, s18, s17
	s_cmp_eq_u32 s6, 0
	s_cselect_b32 s17, s17, s18
	s_add_i32 s17, s17, s16
	v_add_u32_e32 v231, s17, v218
	v_lshl_add_u32 v226, v231, 9, v221
	v_lshl_add_u32 v227, v231, 11, v219
	v_lshl_add_u32 v228, v231, 11, v220
	v_lshlrev_b32_e32 v229, 3, v217
	v_lshl_add_u32 v229, v231, 11, v229
	v_lshlrev_b32_e32 v230, 6, v231
	v_mfma_f32_16x16x32_bf16 v[136:139], v[0:3], v[88:91], 0
	v_mfma_f32_16x16x32_bf16 v[136:139], v[4:7], v[92:95], v[136:139]
	v_mfma_f32_16x16x32_bf16 v[140:143], v[8:11], v[88:91], 0
	v_mfma_f32_16x16x32_bf16 v[140:143], v[12:15], v[92:95], v[140:143]
	v_mfma_f32_16x16x32_bf16 v[144:147], v[16:19], v[96:99], 0
	v_mfma_f32_16x16x32_bf16 v[144:147], v[20:23], v[100:103], v[144:147]
	v_mfma_f32_16x16x32_bf16 v[148:151], v[24:27], v[96:99], 0
	v_mfma_f32_16x16x32_bf16 v[148:151], v[28:31], v[100:103], v[148:151]
	v_lshlrev_b32_e32 v168, 16, v112
	v_and_b32_e32 v169, 0xffff0000, v112
	v_lshlrev_b32_e32 v170, 16, v113
	v_and_b32_e32 v171, 0xffff0000, v113
	v_lshlrev_b32_e32 v172, 16, v114
	v_and_b32_e32 v173, 0xffff0000, v114
	v_lshlrev_b32_e32 v174, 16, v115
	v_and_b32_e32 v175, 0xffff0000, v115
	s_nop 0
	ds_write_b128 v224, v[168:171] offset:0
	ds_write_b128 v224, v[172:175] offset:64
	v_lshlrev_b32_e32 v152, 16, v104
	v_and_b32_e32 v153, 0xffff0000, v104
	v_lshlrev_b32_e32 v154, 16, v105
	v_and_b32_e32 v155, 0xffff0000, v105
	s_nop 0
	v_lshlrev_b32_e32 v156, 16, v106
	v_and_b32_e32 v157, 0xffff0000, v106
	v_lshlrev_b32_e32 v158, 16, v107
	v_and_b32_e32 v159, 0xffff0000, v107
	s_nop 0
	v_lshlrev_b32_e32 v160, 16, v108
	v_and_b32_e32 v161, 0xffff0000, v108
	v_lshlrev_b32_e32 v162, 16, v109
	v_and_b32_e32 v163, 0xffff0000, v109
	s_nop 0
	v_lshlrev_b32_e32 v164, 16, v110
	v_and_b32_e32 v165, 0xffff0000, v110
	v_lshlrev_b32_e32 v166, 16, v111
	v_and_b32_e32 v167, 0xffff0000, v111
	s_nop 0
	v_lshlrev_b32_e32 v192, 16, v120
	v_and_b32_e32 v193, 0xffff0000, v120
	v_lshlrev_b32_e32 v194, 16, v121
	v_and_b32_e32 v195, 0xffff0000, v121
	s_nop 0
	v_pk_mul_f32 v[176:177], v[152:153], v[48:49]
	v_pk_mul_f32 v[178:179], v[154:155], v[50:51]
	v_pk_mul_f32 v[180:181], v[156:157], v[52:53]
	v_pk_mul_f32 v[182:183], v[158:159], v[54:55]
	s_nop 0
	v_pk_mul_f32 v[184:185], v[160:161], v[56:57]
	v_pk_mul_f32 v[186:187], v[162:163], v[58:59]
	v_pk_mul_f32 v[188:189], v[164:165], v[60:61]
	v_pk_mul_f32 v[190:191], v[166:167], v[62:63]
	s_nop 0
	v_pk_mul_f32 v[196:197], v[176:177], v[176:177]
	v_pk_mul_f32 v[198:199], v[178:179], v[178:179]
	v_pk_fma_f32 v[196:197], v[180:181], v[180:181], v[196:197]
	v_pk_fma_f32 v[198:199], v[182:183], v[182:183], v[198:199]
	v_pk_fma_f32 v[196:197], v[184:185], v[184:185], v[196:197]
	v_pk_fma_f32 v[198:199], v[186:187], v[186:187], v[198:199]
	s_nop 0
	v_pk_fma_f32 v[196:197], v[188:189], v[188:189], v[196:197]
	v_pk_fma_f32 v[198:199], v[190:191], v[190:191], v[198:199]
	s_nop 0
	v_pk_add_f32 v[196:197], v[196:197], v[198:199]
	v_mov_b32_e32 v184, v192
	v_mov_b32_e32 v185, v193
	v_mov_b32_e32 v186, v193
	v_mov_b32_e32 v187, v192
	v_mov_b32_e32 v188, v194
	v_mov_b32_e32 v189, v195
	v_mov_b32_e32 v190, v195
	v_mov_b32_e32 v191, v194
	ds_write_b128 v223, v[184:187]
	s_nop 0
	ds_write_b128 v223, v[188:191] offset:16
	s_cmp_eq_u32 s11, 0
	s_cbranch_scc1 .Lrw0_hnbc0
	v_mul_f32_e32 v208, v168, v152
	v_mul_f32_e32 v209, v169, v153
	v_mul_f32_e32 v210, v170, v154
	v_mul_f32_e32 v211, v171, v155
	v_mul_f32_e32 v234, v72, v208
	v_fmac_f32_e32 v234, v73, v209
	v_fmac_f32_e32 v234, v74, v210
	v_fmac_f32_e32 v234, v75, v211
	v_mul_f32_e32 v208, v172, v156
	v_mul_f32_e32 v209, v173, v157
	v_mul_f32_e32 v210, v174, v158
	v_mul_f32_e32 v211, v175, v159
	v_fmac_f32_e32 v234, v76, v208
	v_fmac_f32_e32 v234, v77, v209
	v_fmac_f32_e32 v234, v78, v210
	v_fmac_f32_e32 v234, v79, v211
	v_lshlrev_b32_e32 v204, 16, v116
	v_and_b32_e32 v205, 0xffff0000, v116
	v_lshlrev_b32_e32 v206, 16, v117
	v_and_b32_e32 v207, 0xffff0000, v117
	v_mul_f32_e32 v208, v204, v160
	v_mul_f32_e32 v209, v205, v161
	v_mul_f32_e32 v210, v206, v162
	v_mul_f32_e32 v211, v207, v163
	v_fmac_f32_e32 v234, v80, v208
	v_fmac_f32_e32 v234, v81, v209
	v_fmac_f32_e32 v234, v82, v210
	v_fmac_f32_e32 v234, v83, v211
	v_lshlrev_b32_e32 v204, 16, v118
	v_and_b32_e32 v205, 0xffff0000, v118
	v_lshlrev_b32_e32 v206, 16, v119
	v_and_b32_e32 v207, 0xffff0000, v119
	v_mul_f32_e32 v208, v204, v164
	v_mul_f32_e32 v209, v205, v165
	v_mul_f32_e32 v210, v206, v166
	v_mul_f32_e32 v211, v207, v167
	v_fmac_f32_e32 v234, v84, v208
	v_fmac_f32_e32 v234, v85, v209
	v_fmac_f32_e32 v234, v86, v210
	v_fmac_f32_e32 v234, v87, v211
; __device__ __forceinline__ float sigm(float x) { return __builtin_amdgcn_rcpf(1.f + __expf(-x)); }
; __device__ __forceinline__ void phase_rwkv_scan(const Fr& F, int jr) {
;     ...
; #pragma unroll
;                 for (int reg = 0; reg < 4; ++reg) { const int pp = pt * 16 + lq * 4 + reg;
;                     Wv[pp * 64 + hk] = __expf(-0.60653066f * sigm(w0v[hh] + cw[reg]));
;                     Av[pp * 64 + hk] = sigm(a0v[hh] + ca[reg]); }
;             }
;             LDS_BAR();
;             {
;                 const float kr[8] = {lo_bf(kw.x), hi_bf(kw.x), lo_bf(kw.y), hi_bf(kw.y), lo_bf(kw.z), hi_bf(kw.z), lo_bf(kw.w), hi_bf(kw.w)};
;                 const float rr[8] = {lo_bf(rw.x), hi_bf(rw.x), lo_bf(rw.y), hi_bf(rw.y), lo_bf(rw.z), hi_bf(rw.z), lo_bf(rw.w), hi_bf(rw.w)};
;                 float kq[8]; float ss = 0.f, bon = 0.f;
; #pragma unroll
;                 for (int i = 0; i < 8; ++i) { kq[i] = kr[i] * kkc[i]; ss += kq[i] * kq[i]; bon += rr[i] * kr[i] * rkc[i]; }
;                 ss += dppf<0xB1>(ss); ss += dppf<0x4E>(ss); ss += dppf<0x141>(ss); bon += dppf<0xB1>(bon); bon += dppf<0x4E>(bon); bon += dppf<0x141>(bon);
;                 if (s == 0 && half == 0 && j8 == 0) Bon[((size_t)b * TB + tokof(s, chunk * 64 + p2)) * 16 + h] = bon;
;                 const float inv = 1.f / fmaxf(sqrtf(ss), 1e-12f);
;                 const f32x4 av0 = *(const f32x4*)(Av + p2 * 64 + hk0), av1 = *(const f32x4*)(Av + p2 * 64 + hk0 + 4);
;                 const float av[8] = {av0.x, av0.y, av0.z, av0.w, av1.x, av1.y, av1.z, av1.w};
;                 float o1[8], o2[8], o3[8];
; #pragma unroll
;                 for (int i = 0; i < 8; ++i) { const float kkv = kq[i] * inv; o1[i] = kkv; o2[i] = kkv * av[i]; o3[i] = kr[i] * (1.f + (av[i] - 1.f) * kac[i]); }
;                 const int o = p2 * 64 + hk0;
;                 *(f32x4*)(KK + o) = (f32x4){o1[0], o1[1], o1[2], o1[3]}; *(f32x4*)(KK + o + 4) = (f32x4){o1[4], o1[5], o1[6], o1[7]};
;                 *(f32x4*)(Bv + o) = (f32x4){o2[0], o2[1], o2[2], o2[3]}; *(f32x4*)(Bv + o + 4) = (f32x4){o2[4], o2[5], o2[6], o2[7]};
;                 *(f32x4*)(KD + o) = (f32x4){o3[0], o3[1], o3[2], o3[3]}; *(f32x4*)(KD + o + 4) = (f32x4){o3[4], o3[5], o3[6], o3[7]};
;                 *(f32x4*)(Rr + o) = (f32x4){rr[0], rr[1], rr[2], rr[3]}; *(f32x4*)(Rr + o + 4) = (f32x4){rr[4], rr[5], rr[6], rr[7]};
.Lrw0_hnbc0:
	v_add_f32_e32 v232, v196, v197
	v_mov_b32_e32 v196, v232
	v_pk_add_f32 v[136:137], v[32:33], v[136:137]
	v_pk_add_f32 v[138:139], v[34:35], v[138:139]
	v_pk_add_f32 v[144:145], v[40:41], v[144:145]
	v_permlane16_swap_b32_e32 v232, v196
	v_pk_add_f32 v[146:147], v[42:43], v[146:147]
	v_pk_add_f32 v[140:141], v[36:37], v[140:141]
	v_pk_add_f32 v[142:143], v[38:39], v[142:143]
	v_add_f32_e32 v232, v232, v196
	v_pk_add_f32 v[148:149], v[44:45], v[148:149]
	v_mov_b32_e32 v196, v232
	v_pk_add_f32 v[150:151], v[46:47], v[150:151]
	v_pk_mul_f32 v[136:137], v[136:137], v[122:123]
	v_pk_mul_f32 v[138:139], v[138:139], v[122:123]
	v_permlane32_swap_b32_e32 v232, v196
	v_pk_mul_f32 v[144:145], v[144:145], v[122:123]
	v_pk_mul_f32 v[146:147], v[146:147], v[122:123]
	v_pk_mul_f32 v[140:141], v[140:141], v[122:123]
	v_add_f32_e32 v232, v232, v196
	v_pk_mul_f32 v[142:143], v[142:143], v[122:123]
	v_mul_f32_e32 v197, 0x4f800000, v232
	v_pk_mul_f32 v[148:149], v[148:149], v[122:123]
	v_mov_b32_e32 v198, 0xf800000
	v_pk_mul_f32 v[150:151], v[150:151], v[122:123]
	v_cmp_gt_f32_e32 vcc, v198, v232
	v_exp_f32_e32 v136, v136
	v_exp_f32_e32 v137, v137
	v_exp_f32_e32 v138, v138
	v_cndmask_b32_e32 v196, v232, v197, vcc
	v_exp_f32_e32 v139, v139
	v_sqrt_f32_e32 v197, v196
	v_exp_f32_e32 v144, v144
	v_exp_f32_e32 v145, v145
	v_add_u32_e32 v198, -1, v197
	v_exp_f32_e32 v146, v146
	v_fma_f32 v200, -v198, v197, v196
	v_exp_f32_e32 v147, v147
	v_add_u32_e32 v199, 1, v197
	v_exp_f32_e32 v140, v140
	v_cmp_ge_f32_e64 s[56:57], 0, v200
	v_exp_f32_e32 v141, v141
	v_exp_f32_e32 v142, v142
	v_exp_f32_e32 v143, v143
	v_cndmask_b32_e64 v198, v197, v198, s[56:57]
	v_exp_f32_e32 v148, v148
	v_fma_f32 v197, -v199, v197, v196
	v_exp_f32_e32 v149, v149
	v_cmp_lt_f32_e64 s[56:57], 0, v197
	v_exp_f32_e32 v150, v150
	v_exp_f32_e32 v151, v151
	v_pk_add_f32 v[136:137], v[136:137], 1.0 op_sel_hi:[1,0]
	v_cndmask_b32_e64 v197, v198, v199, s[56:57]
	v_pk_add_f32 v[138:139], v[138:139], 1.0 op_sel_hi:[1,0]
	v_mul_f32_e32 v198, 0x37800000, v197
	v_pk_add_f32 v[144:145], v[144:145], 1.0 op_sel_hi:[1,0]
	v_cndmask_b32_e32 v197, v197, v198, vcc
	v_pk_add_f32 v[146:147], v[146:147], 1.0 op_sel_hi:[1,0]
	v_mov_b32_e32 v198, 0x260
	v_pk_add_f32 v[140:141], v[140:141], 1.0 op_sel_hi:[1,0]
	v_cmp_class_f32_e32 vcc, v196, v198
	v_pk_add_f32 v[142:143], v[142:143], 1.0 op_sel_hi:[1,0]
	v_pk_add_f32 v[148:149], v[148:149], 1.0 op_sel_hi:[1,0]
	v_pk_add_f32 v[150:151], v[150:151], 1.0 op_sel_hi:[1,0]
	v_cndmask_b32_e32 v196, v197, v196, vcc
	v_rcp_f32_e32 v136, v136
	v_max_f32_e32 v196, 0x2b8cbccc, v196
	v_rcp_f32_e32 v137, v137
	v_div_scale_f32 v197, s[56:57], v196, v196, 1.0
	v_rcp_f32_e32 v138, v138
	v_rcp_f32_e32 v198, v197
	v_rcp_f32_e32 v139, v139
	v_rcp_f32_e32 v144, v144
	v_fma_f32 v199, -v197, v198, 1.0
	v_rcp_f32_e32 v145, v145
	v_fmac_f32_e32 v198, v199, v198
	v_rcp_f32_e32 v146, v146
	v_div_scale_f32 v199, vcc, 1.0, v196, 1.0
	v_rcp_f32_e32 v147, v147
	v_mul_f32_e32 v200, v199, v198
	v_rcp_f32_e32 v140, v140
	v_fma_f32 v201, -v197, v200, v199
	v_rcp_f32_e32 v141, v141
	v_fmac_f32_e32 v200, v201, v198
	v_rcp_f32_e32 v142, v142
	v_fma_f32 v197, -v197, v200, v199
	v_rcp_f32_e32 v143, v143
	v_rcp_f32_e32 v148, v148
	v_div_fmas_f32 v197, v197, v198, v200
	v_rcp_f32_e32 v149, v149
	v_div_fixup_f32 v232, v197, v196, 1.0
	v_rcp_f32_e32 v150, v150
	v_rcp_f32_e32 v151, v151
	v_pk_mul_f32 v[136:137], v[136:137], v[124:125]
	v_pk_mul_f32 v[138:139], v[138:139], v[124:125]
	v_pk_mul_f32 v[140:141], v[140:141], v[124:125]
	v_pk_mul_f32 v[142:143], v[142:143], v[124:125]
	v_pk_mul_f32 v[136:137], v[136:137], v[126:127]
	v_pk_mul_f32 v[138:139], v[138:139], v[126:127]
	v_pk_mul_f32 v[140:141], v[140:141], v[126:127]
	v_pk_mul_f32 v[142:143], v[142:143], v[126:127]
	v_exp_f32_e32 v136, v136
	v_exp_f32_e32 v137, v137
	v_exp_f32_e32 v138, v138
	v_exp_f32_e32 v139, v139
	v_exp_f32_e32 v140, v140
	v_exp_f32_e32 v141, v141
	v_exp_f32_e32 v142, v142
	v_exp_f32_e32 v143, v143
	s_nop 0
	ds_write_b128 v222, v[136:139] offset:0
	ds_write_b128 v222, v[140:143] offset:64
	v_pk_mul_f32 v[204:205], v[176:177], v[232:233] op_sel_hi:[1,0]
	v_pk_mul_f32 v[206:207], v[178:179], v[232:233] op_sel_hi:[1,0]
	v_pk_add_f32 v[212:213], v[144:145], -1.0 op_sel_hi:[1,0]
	v_pk_add_f32 v[214:215], v[146:147], -1.0 op_sel_hi:[1,0]
	v_pk_mul_f32 v[208:209], v[204:205], v[144:145]
	v_pk_mul_f32 v[210:211], v[206:207], v[146:147]
	v_pk_fma_f32 v[212:213], v[64:65], v[212:213], 1.0 op_sel_hi:[1,1,0]
	v_pk_fma_f32 v[214:215], v[66:67], v[214:215], 1.0 op_sel_hi:[1,1,0]
	ds_write_b128 v222, v[204:207] offset:17408
	v_pk_mul_f32 v[212:213], v[212:213], v[152:153]
	v_pk_mul_f32 v[214:215], v[214:215], v[154:155]
	ds_write_b128 v222, v[208:211] offset:34816
	ds_write_b128 v222, v[212:215] offset:52224
	v_pk_mul_f32 v[184:185], v[180:181], v[232:233] op_sel_hi:[1,0]
	v_pk_mul_f32 v[186:187], v[182:183], v[232:233] op_sel_hi:[1,0]
	v_pk_add_f32 v[160:161], v[148:149], -1.0 op_sel_hi:[1,0]
	v_pk_add_f32 v[162:163], v[150:151], -1.0 op_sel_hi:[1,0]
	v_pk_mul_f32 v[188:189], v[184:185], v[148:149]
	v_pk_mul_f32 v[190:191], v[186:187], v[150:151]
	v_pk_fma_f32 v[160:161], v[68:69], v[160:161], 1.0 op_sel_hi:[1,1,0]
	v_pk_fma_f32 v[162:163], v[70:71], v[162:163], 1.0 op_sel_hi:[1,1,0]
	ds_write_b128 v222, v[184:187] offset:17472
	v_pk_mul_f32 v[160:161], v[160:161], v[156:157]
	v_pk_mul_f32 v[162:163], v[162:163], v[158:159]
	ds_write_b128 v222, v[188:191] offset:34880
	ds_write_b128 v222, v[160:163] offset:52288
	s_cmp_eq_u32 s11, 0
	s_cbranch_scc1 .Lrw0_hnb0
	v_mov_b32_e32 v196, v234
	s_nop 1
	v_permlane16_swap_b32_e32 v234, v196
	s_nop 1
	v_add_f32_e32 v234, v234, v196
	v_mov_b32_e32 v196, v234
	s_nop 1
	v_permlane32_swap_b32_e32 v234, v196
	s_nop 1
	v_add_f32_e32 v234, v234, v196
	v_cmp_gt_u32_e32 vcc, 16, v130
	s_and_saveexec_b64 s[56:57], vcc
	global_store_dword v225, v234, s[44:45]
	s_mov_b64 exec, s[56:57]
; #define LDS_BAR() asm volatile("s_waitcnt lgkmcnt(0)\n\ts_barrier" ::: "memory")
; __device__ __forceinline__ void phase_rwkv_scan(const Fr& F, int jr) {
;     ...
;             LDS_BAR();
;             {
;                 float* Ypw = Yp + wave * 1024;
;                 unsigned a1 = (unsigned)(size_t)(__attribute__((address_space(3))) float*)(Wv + ks), a2 = (unsigned)(size_t)(__attribute__((address_space(3))) float*)(Rr + ks),
;                          a3 = (unsigned)(size_t)(__attribute__((address_space(3))) float*)(Vv + rloc), a4 = (unsigned)(size_t)(__attribute__((address_space(3))) float*)(Ypw + lane);
;                 asm volatile("" : "+v"(a1), "+v"(a2), "+v"(a3), "+v"(a4));
;                 typedef const __attribute__((address_space(3))) f32x4* lp4; typedef const __attribute__((address_space(3))) float* lp1; typedef __attribute__((address_space(3))) float* lw1;
;                 const lp4 PW = (lp4)a1, PR = (lp4)a2; const lp1 PV = (lp1)a3; const lw1 PY = (lw1)a4;
;                 f32x4 w4 = PW[0], k4 = PW[1024], b4 = PW[2048], d4 = PW[3072], r4 = PR[0];
;                 float vv = PV[0];
;                 for (int pg = 0; pg < 64; pg += 16) {
; #pragma unroll
;                     for (int pi = 0; pi < 16; ++pi) {
;                         const int p = pg + pi, pn = p < 63 ? p + 1 : 63;
;                         const f32x4 w4n = PW[pn * 16], k4n = PW[1024 + pn * 16], b4n = PW[2048 + pn * 16], d4n = PW[3072 + pn * 16], r4n = PR[pn * 16];
;                         const float vvn = PV[pn * 32];
;                         f32x2 t = S01 * k4.xy; t = S23 * k4.zw + t; float sa = t.x + t.y;
;                         sa += dppf<0x128>(sa);
;                         const f32x2 dv01 = d4.xy * vv, dv23 = d4.zw * vv;
;                         sa += dppf<0x124>(sa);
;                         const f32x2 e01 = S01 * w4.xy + dv01;
;                         sa += dppf<0x122>(sa);
;                         const f32x2 e23 = S23 * w4.zw + dv23;
;                         sa += dppf<0x121>(sa);
;                         S01 = e01 - b4.xy * sa; S23 = e23 - b4.zw * sa;
;                         f32x2 u = S01 * r4.xy; u = S23 * r4.zw + u;
;                         PY[pi * 64] = u.x + u.y;
;                         w4 = w4n; k4 = k4n; b4 = b4n; d4 = d4n; r4 = r4n; vv = vvn;
.Lrw0_hnb0:
	s_waitcnt lgkmcnt(0)
	s_barrier
	s_cmp_gt_u32 s68, 3
	s_cbranch_scc1 .Lrw0_skip
	s_mov_b32 s87, 0
	v_mov_b32_e32 v194, v244
	v_mov_b32_e32 v195, v245
	v_mov_b32_e32 v196, v246
	ds_read_b128 v[140:143], v244 offset:17408
	ds_read_b64 v[156:157], v246
	ds_read_b128 v[148:151], v244 offset:52224
	ds_read_b128 v[136:139], v244
	ds_read_b128 v[144:147], v244 offset:34816
	ds_read_b128 v[152:155], v245
	s_add_i32 s91, s10, -1
	s_lshl_b32 s92, s91, 6
	s_cmp_lt_u32 s91, 4
	s_movk_i32 s93, 0x11ff
	s_cselect_b32 s93, 0xff, s93
	s_sub_i32 s93, s93, s92
	s_cmp_eq_u32 s6, 0
	s_cselect_b32 s90, s92, s93
	s_cselect_b32 s94, 16, -16
	s_waitcnt lgkmcnt(0)
.Lrw0_group:
	ds_read_b128 v[164:167], v194 offset:17680
	ds_read_b64 v[158:159], v196 offset:272
	ds_read_b128 v[172:175], v194 offset:52496
	ds_read_b128 v[160:163], v194 offset:272
	ds_read_b128 v[168:171], v194 offset:35088
	v_pk_mul_f32 v[180:181], v[236:237], v[140:141] op_sel_hi:[1,0]
	v_pk_mul_f32 v[186:187], v[156:157], v[148:149] op_sel_hi:[1,0]
	v_pk_fma_f32 v[180:181], v[238:239], v[140:141], v[180:181] op_sel:[0,1,0]
	v_pk_mul_f32 v[188:189], v[156:157], v[148:149] op_sel:[0,1]
	v_pk_fma_f32 v[180:181], v[240:241], v[142:143], v[180:181] op_sel_hi:[1,0,1]
	v_pk_mul_f32 v[190:191], v[156:157], v[150:151] op_sel_hi:[1,0]
	v_pk_fma_f32 v[180:181], v[242:243], v[142:143], v[180:181] op_sel:[0,1,0]
	v_pk_mul_f32 v[192:193], v[156:157], v[150:151] op_sel:[0,1]
	s_nop 0
	v_add_f32_dpp v184, v181, v180 row_ror:8 row_mask:0xf bank_mask:0xf
	v_pk_fma_f32 v[186:187], v[236:237], v[136:137], v[186:187] op_sel_hi:[1,0,1]
	v_pk_fma_f32 v[188:189], v[238:239], v[136:137], v[188:189] op_sel:[0,1,0]
	v_add_f32_dpp v184, v184, v184 quad_perm:[1,0,3,2] row_mask:0xf bank_mask:0xf
	v_pk_fma_f32 v[190:191], v[240:241], v[138:139], v[190:191] op_sel_hi:[1,0,1]
	v_pk_fma_f32 v[192:193], v[242:243], v[138:139], v[192:193] op_sel:[0,1,0]
	v_add_f32_dpp v184, v184, v184 quad_perm:[2,3,0,1] row_mask:0xf bank_mask:0xf
	ds_read_b128 v[176:179], v195 offset:272
	s_nop 0
	v_add_f32_dpp v184, v184, v184 row_half_mirror row_mask:0xf bank_mask:0xf
	s_nop 1
	v_mov_b32_dpp v185, v184 row_ror:8 row_mask:0xf bank_mask:0xf
	s_nop 0
	v_pk_fma_f32 v[236:237], v[144:145], v[184:185], v[186:187] op_sel_hi:[0,1,1] neg_lo:[1,0,0] neg_hi:[1,0,0]
	v_pk_fma_f32 v[238:239], v[144:145], v[184:185], v[188:189] op_sel:[1,0,0] neg_lo:[1,0,0] neg_hi:[1,0,0]
	v_pk_fma_f32 v[240:241], v[146:147], v[184:185], v[190:191] op_sel_hi:[0,1,1] neg_lo:[1,0,0] neg_hi:[1,0,0]
	v_pk_fma_f32 v[242:243], v[146:147], v[184:185], v[192:193] op_sel:[1,0,0] neg_lo:[1,0,0] neg_hi:[1,0,0]
	ds_read_b128 v[140:143], v194 offset:17952
	ds_read_b64 v[156:157], v196 offset:544
	ds_read_b128 v[148:151], v194 offset:52768
	ds_read_b128 v[136:139], v194 offset:544
	ds_read_b128 v[144:147], v194 offset:35360
	s_waitcnt lgkmcnt(6)
	v_pk_mul_f32 v[180:181], v[236:237], v[164:165] op_sel_hi:[1,0]
	v_pk_mul_f32 v[182:183], v[236:237], v[152:153] op_sel_hi:[1,0]
	v_pk_fma_f32 v[180:181], v[238:239], v[164:165], v[180:181] op_sel:[0,1,0]
	v_pk_fma_f32 v[182:183], v[238:239], v[152:153], v[182:183] op_sel:[0,1,0]
	v_pk_fma_f32 v[180:181], v[240:241], v[166:167], v[180:181] op_sel_hi:[1,0,1]
	v_pk_fma_f32 v[182:183], v[240:241], v[154:155], v[182:183] op_sel_hi:[1,0,1]
	v_pk_fma_f32 v[180:181], v[242:243], v[166:167], v[180:181] op_sel:[0,1,0]
	v_pk_fma_f32 v[182:183], v[242:243], v[154:155], v[182:183] op_sel:[0,1,0]
	v_pk_mul_f32 v[186:187], v[158:159], v[172:173] op_sel_hi:[1,0]
	v_add_f32_dpp v184, v181, v180 row_ror:8 row_mask:0xf bank_mask:0xf
	v_pk_mul_f32 v[188:189], v[158:159], v[172:173] op_sel:[0,1]
	v_pk_mul_f32 v[190:191], v[158:159], v[174:175] op_sel_hi:[1,0]
	v_add_f32_dpp v184, v184, v184 quad_perm:[1,0,3,2] row_mask:0xf bank_mask:0xf
	v_pk_mul_f32 v[192:193], v[158:159], v[174:175] op_sel:[0,1]
	ds_read_b128 v[152:155], v195 offset:544
	v_add_f32_dpp v184, v184, v184 quad_perm:[2,3,0,1] row_mask:0xf bank_mask:0xf
	v_pk_fma_f32 v[186:187], v[236:237], v[160:161], v[186:187] op_sel_hi:[1,0,1]
	v_pk_fma_f32 v[188:189], v[238:239], v[160:161], v[188:189] op_sel:[0,1,0]
	v_add_f32_dpp v184, v184, v184 row_half_mirror row_mask:0xf bank_mask:0xf
	v_pk_fma_f32 v[190:191], v[240:241], v[162:163], v[190:191] op_sel_hi:[1,0,1]
	v_pk_fma_f32 v[192:193], v[242:243], v[162:163], v[192:193] op_sel:[0,1,0]
	v_mov_b32_dpp v185, v184 row_ror:8 row_mask:0xf bank_mask:0xf
	ds_write_b64 v247, v[182:183] offset:0
	v_pk_fma_f32 v[236:237], v[168:169], v[184:185], v[186:187] op_sel_hi:[0,1,1] neg_lo:[1,0,0] neg_hi:[1,0,0]
	v_pk_fma_f32 v[238:239], v[168:169], v[184:185], v[188:189] op_sel:[1,0,0] neg_lo:[1,0,0] neg_hi:[1,0,0]
	v_pk_fma_f32 v[240:241], v[170:171], v[184:185], v[190:191] op_sel_hi:[0,1,1] neg_lo:[1,0,0] neg_hi:[1,0,0]
	v_pk_fma_f32 v[242:243], v[170:171], v[184:185], v[192:193] op_sel:[1,0,0] neg_lo:[1,0,0] neg_hi:[1,0,0]
	ds_read_b128 v[164:167], v194 offset:18224
	ds_read_b64 v[158:159], v196 offset:816
	ds_read_b128 v[172:175], v194 offset:53040
	ds_read_b128 v[160:163], v194 offset:816
	ds_read_b128 v[168:171], v194 offset:35632
	s_waitcnt lgkmcnt(7)
; template <int CTRL> __device__ __forceinline__ float dppf(float x) { return __builtin_bit_cast(float, __builtin_amdgcn_update_dpp(0, __builtin_bit_cast(int, x), CTRL, 0xF, 0xF, false)); }
; __device__ __forceinline__ void phase_rwkv_scan(const Fr& F, int jr) {
;     ...
;                 for (int pg = 0; pg < 64; pg += 16) {
; #pragma unroll
;                     for (int pi = 0; pi < 16; ++pi) {
;                         const int p = pg + pi, pn = p < 63 ? p + 1 : 63;
;                         const f32x4 w4n = PW[pn * 16], k4n = PW[1024 + pn * 16], b4n = PW[2048 + pn * 16], d4n = PW[3072 + pn * 16], r4n = PR[pn * 16];
;                         const float vvn = PV[pn * 32];
;                         f32x2 t = S01 * k4.xy; t = S23 * k4.zw + t; float sa = t.x + t.y;
;                         sa += dppf<0x128>(sa);
;                         const f32x2 dv01 = d4.xy * vv, dv23 = d4.zw * vv;
;                         sa += dppf<0x124>(sa);
;                         const f32x2 e01 = S01 * w4.xy + dv01;
;                         sa += dppf<0x122>(sa);
;                         const f32x2 e23 = S23 * w4.zw + dv23;
;                         sa += dppf<0x121>(sa);
;                         S01 = e01 - b4.xy * sa; S23 = e23 - b4.zw * sa;
;                         f32x2 u = S01 * r4.xy; u = S23 * r4.zw + u;
;                         PY[pi * 64] = u.x + u.y;
;                         w4 = w4n; k4 = k4n; b4 = b4n; d4 = d4n; r4 = r4n; vv = vvn;
	v_pk_mul_f32 v[180:181], v[236:237], v[140:141] op_sel_hi:[1,0]
	v_pk_mul_f32 v[182:183], v[236:237], v[176:177] op_sel_hi:[1,0]
	v_pk_fma_f32 v[180:181], v[238:239], v[140:141], v[180:181] op_sel:[0,1,0]
	v_pk_fma_f32 v[182:183], v[238:239], v[176:177], v[182:183] op_sel:[0,1,0]
	v_pk_fma_f32 v[180:181], v[240:241], v[142:143], v[180:181] op_sel_hi:[1,0,1]
	v_pk_fma_f32 v[182:183], v[240:241], v[178:179], v[182:183] op_sel_hi:[1,0,1]
	v_pk_fma_f32 v[180:181], v[242:243], v[142:143], v[180:181] op_sel:[0,1,0]
	v_pk_fma_f32 v[182:183], v[242:243], v[178:179], v[182:183] op_sel:[0,1,0]
	v_pk_mul_f32 v[186:187], v[156:157], v[148:149] op_sel_hi:[1,0]
	v_add_f32_dpp v184, v181, v180 row_ror:8 row_mask:0xf bank_mask:0xf
	v_pk_mul_f32 v[188:189], v[156:157], v[148:149] op_sel:[0,1]
	v_pk_mul_f32 v[190:191], v[156:157], v[150:151] op_sel_hi:[1,0]
	v_add_f32_dpp v184, v184, v184 quad_perm:[1,0,3,2] row_mask:0xf bank_mask:0xf
	v_pk_mul_f32 v[192:193], v[156:157], v[150:151] op_sel:[0,1]
	ds_read_b128 v[176:179], v195 offset:816
	v_add_f32_dpp v184, v184, v184 quad_perm:[2,3,0,1] row_mask:0xf bank_mask:0xf
	v_pk_fma_f32 v[186:187], v[236:237], v[136:137], v[186:187] op_sel_hi:[1,0,1]
	v_pk_fma_f32 v[188:189], v[238:239], v[136:137], v[188:189] op_sel:[0,1,0]
	v_add_f32_dpp v184, v184, v184 row_half_mirror row_mask:0xf bank_mask:0xf
	v_pk_fma_f32 v[190:191], v[240:241], v[138:139], v[190:191] op_sel_hi:[1,0,1]
	v_pk_fma_f32 v[192:193], v[242:243], v[138:139], v[192:193] op_sel:[0,1,0]
	v_mov_b32_dpp v185, v184 row_ror:8 row_mask:0xf bank_mask:0xf
	ds_write_b64 v247, v[182:183] offset:576
	v_pk_fma_f32 v[236:237], v[144:145], v[184:185], v[186:187] op_sel_hi:[0,1,1] neg_lo:[1,0,0] neg_hi:[1,0,0]
	v_pk_fma_f32 v[238:239], v[144:145], v[184:185], v[188:189] op_sel:[1,0,0] neg_lo:[1,0,0] neg_hi:[1,0,0]
	v_pk_fma_f32 v[240:241], v[146:147], v[184:185], v[190:191] op_sel_hi:[0,1,1] neg_lo:[1,0,0] neg_hi:[1,0,0]
	v_pk_fma_f32 v[242:243], v[146:147], v[184:185], v[192:193] op_sel:[1,0,0] neg_lo:[1,0,0] neg_hi:[1,0,0]
	ds_read_b128 v[140:143], v194 offset:18496
	ds_read_b64 v[156:157], v196 offset:1088
	ds_read_b128 v[148:151], v194 offset:53312
	ds_read_b128 v[136:139], v194 offset:1088
	ds_read_b128 v[144:147], v194 offset:35904
	s_waitcnt lgkmcnt(7)
	v_pk_mul_f32 v[180:181], v[236:237], v[164:165] op_sel_hi:[1,0]
	v_pk_mul_f32 v[182:183], v[236:237], v[152:153] op_sel_hi:[1,0]
	v_pk_fma_f32 v[180:181], v[238:239], v[164:165], v[180:181] op_sel:[0,1,0]
	v_pk_fma_f32 v[182:183], v[238:239], v[152:153], v[182:183] op_sel:[0,1,0]
	v_pk_fma_f32 v[180:181], v[240:241], v[166:167], v[180:181] op_sel_hi:[1,0,1]
	v_pk_fma_f32 v[182:183], v[240:241], v[154:155], v[182:183] op_sel_hi:[1,0,1]
	v_pk_fma_f32 v[180:181], v[242:243], v[166:167], v[180:181] op_sel:[0,1,0]
	v_pk_fma_f32 v[182:183], v[242:243], v[154:155], v[182:183] op_sel:[0,1,0]
	v_pk_mul_f32 v[186:187], v[158:159], v[172:173] op_sel_hi:[1,0]
	v_add_f32_dpp v184, v181, v180 row_ror:8 row_mask:0xf bank_mask:0xf
	v_pk_mul_f32 v[188:189], v[158:159], v[172:173] op_sel:[0,1]
	v_pk_mul_f32 v[190:191], v[158:159], v[174:175] op_sel_hi:[1,0]
	v_add_f32_dpp v184, v184, v184 quad_perm:[1,0,3,2] row_mask:0xf bank_mask:0xf
	v_pk_mul_f32 v[192:193], v[158:159], v[174:175] op_sel:[0,1]
	ds_read_b128 v[152:155], v195 offset:1088
	v_add_f32_dpp v184, v184, v184 quad_perm:[2,3,0,1] row_mask:0xf bank_mask:0xf
	v_pk_fma_f32 v[186:187], v[236:237], v[160:161], v[186:187] op_sel_hi:[1,0,1]
	v_pk_fma_f32 v[188:189], v[238:239], v[160:161], v[188:189] op_sel:[0,1,0]
	v_add_f32_dpp v184, v184, v184 row_half_mirror row_mask:0xf bank_mask:0xf
	v_pk_fma_f32 v[190:191], v[240:241], v[162:163], v[190:191] op_sel_hi:[1,0,1]
	v_pk_fma_f32 v[192:193], v[242:243], v[162:163], v[192:193] op_sel:[0,1,0]
	v_mov_b32_dpp v185, v184 row_ror:8 row_mask:0xf bank_mask:0xf
	ds_write_b64 v247, v[182:183] offset:1152
	v_pk_fma_f32 v[236:237], v[168:169], v[184:185], v[186:187] op_sel_hi:[0,1,1] neg_lo:[1,0,0] neg_hi:[1,0,0]
	v_pk_fma_f32 v[238:239], v[168:169], v[184:185], v[188:189] op_sel:[1,0,0] neg_lo:[1,0,0] neg_hi:[1,0,0]
	v_pk_fma_f32 v[240:241], v[170:171], v[184:185], v[190:191] op_sel_hi:[0,1,1] neg_lo:[1,0,0] neg_hi:[1,0,0]
	v_pk_fma_f32 v[242:243], v[170:171], v[184:185], v[192:193] op_sel:[1,0,0] neg_lo:[1,0,0] neg_hi:[1,0,0]
	ds_read_b128 v[164:167], v194 offset:18768
	ds_read_b64 v[158:159], v196 offset:1360
	ds_read_b128 v[172:175], v194 offset:53584
	ds_read_b128 v[160:163], v194 offset:1360
	ds_read_b128 v[168:171], v194 offset:36176
	s_waitcnt lgkmcnt(7)
; template <int CTRL> __device__ __forceinline__ float dppf(float x) { return __builtin_bit_cast(float, __builtin_amdgcn_update_dpp(0, __builtin_bit_cast(int, x), CTRL, 0xF, 0xF, false)); }
; __device__ __forceinline__ void phase_rwkv_scan(const Fr& F, int jr) {
;     ...
;                 for (int pg = 0; pg < 64; pg += 16) {
; #pragma unroll
;                     for (int pi = 0; pi < 16; ++pi) {
;                         const int p = pg + pi, pn = p < 63 ? p + 1 : 63;
;                         const f32x4 w4n = PW[pn * 16], k4n = PW[1024 + pn * 16], b4n = PW[2048 + pn * 16], d4n = PW[3072 + pn * 16], r4n = PR[pn * 16];
;                         const float vvn = PV[pn * 32];
;                         f32x2 t = S01 * k4.xy; t = S23 * k4.zw + t; float sa = t.x + t.y;
;                         sa += dppf<0x128>(sa);
;                         const f32x2 dv01 = d4.xy * vv, dv23 = d4.zw * vv;
;                         sa += dppf<0x124>(sa);
;                         const f32x2 e01 = S01 * w4.xy + dv01;
;                         sa += dppf<0x122>(sa);
;                         const f32x2 e23 = S23 * w4.zw + dv23;
;                         sa += dppf<0x121>(sa);
;                         S01 = e01 - b4.xy * sa; S23 = e23 - b4.zw * sa;
;                         f32x2 u = S01 * r4.xy; u = S23 * r4.zw + u;
;                         PY[pi * 64] = u.x + u.y;
;                         w4 = w4n; k4 = k4n; b4 = b4n; d4 = d4n; r4 = r4n; vv = vvn;
	v_pk_mul_f32 v[180:181], v[236:237], v[140:141] op_sel_hi:[1,0]
	v_pk_mul_f32 v[182:183], v[236:237], v[176:177] op_sel_hi:[1,0]
	v_pk_fma_f32 v[180:181], v[238:239], v[140:141], v[180:181] op_sel:[0,1,0]
	v_pk_fma_f32 v[182:183], v[238:239], v[176:177], v[182:183] op_sel:[0,1,0]
	v_pk_fma_f32 v[180:181], v[240:241], v[142:143], v[180:181] op_sel_hi:[1,0,1]
	v_pk_fma_f32 v[182:183], v[240:241], v[178:179], v[182:183] op_sel_hi:[1,0,1]
	v_pk_fma_f32 v[180:181], v[242:243], v[142:143], v[180:181] op_sel:[0,1,0]
	v_pk_fma_f32 v[182:183], v[242:243], v[178:179], v[182:183] op_sel:[0,1,0]
	v_pk_mul_f32 v[186:187], v[156:157], v[148:149] op_sel_hi:[1,0]
	v_add_f32_dpp v184, v181, v180 row_ror:8 row_mask:0xf bank_mask:0xf
	v_pk_mul_f32 v[188:189], v[156:157], v[148:149] op_sel:[0,1]
	v_pk_mul_f32 v[190:191], v[156:157], v[150:151] op_sel_hi:[1,0]
	v_add_f32_dpp v184, v184, v184 quad_perm:[1,0,3,2] row_mask:0xf bank_mask:0xf
	v_pk_mul_f32 v[192:193], v[156:157], v[150:151] op_sel:[0,1]
	ds_read_b128 v[176:179], v195 offset:1360
	v_add_f32_dpp v184, v184, v184 quad_perm:[2,3,0,1] row_mask:0xf bank_mask:0xf
	v_pk_fma_f32 v[186:187], v[236:237], v[136:137], v[186:187] op_sel_hi:[1,0,1]
	v_pk_fma_f32 v[188:189], v[238:239], v[136:137], v[188:189] op_sel:[0,1,0]
	v_add_f32_dpp v184, v184, v184 row_half_mirror row_mask:0xf bank_mask:0xf
	v_pk_fma_f32 v[190:191], v[240:241], v[138:139], v[190:191] op_sel_hi:[1,0,1]
	v_pk_fma_f32 v[192:193], v[242:243], v[138:139], v[192:193] op_sel:[0,1,0]
	v_mov_b32_dpp v185, v184 row_ror:8 row_mask:0xf bank_mask:0xf
	ds_write_b64 v247, v[182:183] offset:1728
	v_pk_fma_f32 v[236:237], v[144:145], v[184:185], v[186:187] op_sel_hi:[0,1,1] neg_lo:[1,0,0] neg_hi:[1,0,0]
	v_pk_fma_f32 v[238:239], v[144:145], v[184:185], v[188:189] op_sel:[1,0,0] neg_lo:[1,0,0] neg_hi:[1,0,0]
	v_pk_fma_f32 v[240:241], v[146:147], v[184:185], v[190:191] op_sel_hi:[0,1,1] neg_lo:[1,0,0] neg_hi:[1,0,0]
	v_pk_fma_f32 v[242:243], v[146:147], v[184:185], v[192:193] op_sel:[1,0,0] neg_lo:[1,0,0] neg_hi:[1,0,0]
	ds_read_b128 v[140:143], v194 offset:19040
	ds_read_b64 v[156:157], v196 offset:1632
	ds_read_b128 v[148:151], v194 offset:53856
	ds_read_b128 v[136:139], v194 offset:1632
	ds_read_b128 v[144:147], v194 offset:36448
	s_waitcnt lgkmcnt(7)
	v_pk_mul_f32 v[180:181], v[236:237], v[164:165] op_sel_hi:[1,0]
	v_pk_mul_f32 v[182:183], v[236:237], v[152:153] op_sel_hi:[1,0]
	v_pk_fma_f32 v[180:181], v[238:239], v[164:165], v[180:181] op_sel:[0,1,0]
	v_pk_fma_f32 v[182:183], v[238:239], v[152:153], v[182:183] op_sel:[0,1,0]
	v_pk_fma_f32 v[180:181], v[240:241], v[166:167], v[180:181] op_sel_hi:[1,0,1]
	v_pk_fma_f32 v[182:183], v[240:241], v[154:155], v[182:183] op_sel_hi:[1,0,1]
	v_pk_fma_f32 v[180:181], v[242:243], v[166:167], v[180:181] op_sel:[0,1,0]
	v_pk_fma_f32 v[182:183], v[242:243], v[154:155], v[182:183] op_sel:[0,1,0]
	v_pk_mul_f32 v[186:187], v[158:159], v[172:173] op_sel_hi:[1,0]
	v_add_f32_dpp v184, v181, v180 row_ror:8 row_mask:0xf bank_mask:0xf
	v_pk_mul_f32 v[188:189], v[158:159], v[172:173] op_sel:[0,1]
	v_pk_mul_f32 v[190:191], v[158:159], v[174:175] op_sel_hi:[1,0]
	v_add_f32_dpp v184, v184, v184 quad_perm:[1,0,3,2] row_mask:0xf bank_mask:0xf
	v_pk_mul_f32 v[192:193], v[158:159], v[174:175] op_sel:[0,1]
	ds_read_b128 v[152:155], v195 offset:1632
	v_add_f32_dpp v184, v184, v184 quad_perm:[2,3,0,1] row_mask:0xf bank_mask:0xf
	v_pk_fma_f32 v[186:187], v[236:237], v[160:161], v[186:187] op_sel_hi:[1,0,1]
	v_pk_fma_f32 v[188:189], v[238:239], v[160:161], v[188:189] op_sel:[0,1,0]
	v_add_f32_dpp v184, v184, v184 row_half_mirror row_mask:0xf bank_mask:0xf
	v_pk_fma_f32 v[190:191], v[240:241], v[162:163], v[190:191] op_sel_hi:[1,0,1]
	v_pk_fma_f32 v[192:193], v[242:243], v[162:163], v[192:193] op_sel:[0,1,0]
	v_mov_b32_dpp v185, v184 row_ror:8 row_mask:0xf bank_mask:0xf
	ds_write_b64 v247, v[182:183] offset:2304
	v_pk_fma_f32 v[236:237], v[168:169], v[184:185], v[186:187] op_sel_hi:[0,1,1] neg_lo:[1,0,0] neg_hi:[1,0,0]
	v_pk_fma_f32 v[238:239], v[168:169], v[184:185], v[188:189] op_sel:[1,0,0] neg_lo:[1,0,0] neg_hi:[1,0,0]
	v_pk_fma_f32 v[240:241], v[170:171], v[184:185], v[190:191] op_sel_hi:[0,1,1] neg_lo:[1,0,0] neg_hi:[1,0,0]
	v_pk_fma_f32 v[242:243], v[170:171], v[184:185], v[192:193] op_sel:[1,0,0] neg_lo:[1,0,0] neg_hi:[1,0,0]
	ds_read_b128 v[164:167], v194 offset:19312
	ds_read_b64 v[158:159], v196 offset:1904
	ds_read_b128 v[172:175], v194 offset:54128
	ds_read_b128 v[160:163], v194 offset:1904
	ds_read_b128 v[168:171], v194 offset:36720
	s_waitcnt lgkmcnt(7)
; template <int CTRL> __device__ __forceinline__ float dppf(float x) { return __builtin_bit_cast(float, __builtin_amdgcn_update_dpp(0, __builtin_bit_cast(int, x), CTRL, 0xF, 0xF, false)); }
; __device__ __forceinline__ void phase_rwkv_scan(const Fr& F, int jr) {
;     ...
;                 for (int pg = 0; pg < 64; pg += 16) {
; #pragma unroll
;                     for (int pi = 0; pi < 16; ++pi) {
;                         const int p = pg + pi, pn = p < 63 ? p + 1 : 63;
;                         const f32x4 w4n = PW[pn * 16], k4n = PW[1024 + pn * 16], b4n = PW[2048 + pn * 16], d4n = PW[3072 + pn * 16], r4n = PR[pn * 16];
;                         const float vvn = PV[pn * 32];
;                         f32x2 t = S01 * k4.xy; t = S23 * k4.zw + t; float sa = t.x + t.y;
;                         sa += dppf<0x128>(sa);
;                         const f32x2 dv01 = d4.xy * vv, dv23 = d4.zw * vv;
;                         sa += dppf<0x124>(sa);
;                         const f32x2 e01 = S01 * w4.xy + dv01;
;                         sa += dppf<0x122>(sa);
;                         const f32x2 e23 = S23 * w4.zw + dv23;
;                         sa += dppf<0x121>(sa);
;                         S01 = e01 - b4.xy * sa; S23 = e23 - b4.zw * sa;
;                         f32x2 u = S01 * r4.xy; u = S23 * r4.zw + u;
;                         PY[pi * 64] = u.x + u.y;
;                         w4 = w4n; k4 = k4n; b4 = b4n; d4 = d4n; r4 = r4n; vv = vvn;
	v_pk_mul_f32 v[180:181], v[236:237], v[140:141] op_sel_hi:[1,0]
	v_pk_mul_f32 v[182:183], v[236:237], v[176:177] op_sel_hi:[1,0]
	v_pk_fma_f32 v[180:181], v[238:239], v[140:141], v[180:181] op_sel:[0,1,0]
	v_pk_fma_f32 v[182:183], v[238:239], v[176:177], v[182:183] op_sel:[0,1,0]
	v_pk_fma_f32 v[180:181], v[240:241], v[142:143], v[180:181] op_sel_hi:[1,0,1]
	v_pk_fma_f32 v[182:183], v[240:241], v[178:179], v[182:183] op_sel_hi:[1,0,1]
	v_pk_fma_f32 v[180:181], v[242:243], v[142:143], v[180:181] op_sel:[0,1,0]
	v_pk_fma_f32 v[182:183], v[242:243], v[178:179], v[182:183] op_sel:[0,1,0]
	v_pk_mul_f32 v[186:187], v[156:157], v[148:149] op_sel_hi:[1,0]
	v_add_f32_dpp v184, v181, v180 row_ror:8 row_mask:0xf bank_mask:0xf
	v_pk_mul_f32 v[188:189], v[156:157], v[148:149] op_sel:[0,1]
	v_pk_mul_f32 v[190:191], v[156:157], v[150:151] op_sel_hi:[1,0]
	v_add_f32_dpp v184, v184, v184 quad_perm:[1,0,3,2] row_mask:0xf bank_mask:0xf
	v_pk_mul_f32 v[192:193], v[156:157], v[150:151] op_sel:[0,1]
	ds_read_b128 v[176:179], v195 offset:1904
	v_add_f32_dpp v184, v184, v184 quad_perm:[2,3,0,1] row_mask:0xf bank_mask:0xf
	v_pk_fma_f32 v[186:187], v[236:237], v[136:137], v[186:187] op_sel_hi:[1,0,1]
	v_pk_fma_f32 v[188:189], v[238:239], v[136:137], v[188:189] op_sel:[0,1,0]
	v_add_f32_dpp v184, v184, v184 row_half_mirror row_mask:0xf bank_mask:0xf
	v_pk_fma_f32 v[190:191], v[240:241], v[138:139], v[190:191] op_sel_hi:[1,0,1]
	v_pk_fma_f32 v[192:193], v[242:243], v[138:139], v[192:193] op_sel:[0,1,0]
	v_mov_b32_dpp v185, v184 row_ror:8 row_mask:0xf bank_mask:0xf
	ds_write_b64 v247, v[182:183] offset:2880
	v_pk_fma_f32 v[236:237], v[144:145], v[184:185], v[186:187] op_sel_hi:[0,1,1] neg_lo:[1,0,0] neg_hi:[1,0,0]
	v_pk_fma_f32 v[238:239], v[144:145], v[184:185], v[188:189] op_sel:[1,0,0] neg_lo:[1,0,0] neg_hi:[1,0,0]
	v_pk_fma_f32 v[240:241], v[146:147], v[184:185], v[190:191] op_sel_hi:[0,1,1] neg_lo:[1,0,0] neg_hi:[1,0,0]
	v_pk_fma_f32 v[242:243], v[146:147], v[184:185], v[192:193] op_sel:[1,0,0] neg_lo:[1,0,0] neg_hi:[1,0,0]
	ds_read_b128 v[140:143], v194 offset:19584
	ds_read_b64 v[156:157], v196 offset:2176
	ds_read_b128 v[148:151], v194 offset:54400
	ds_read_b128 v[136:139], v194 offset:2176
	ds_read_b128 v[144:147], v194 offset:36992
	s_waitcnt lgkmcnt(7)
	v_pk_mul_f32 v[180:181], v[236:237], v[164:165] op_sel_hi:[1,0]
	v_pk_mul_f32 v[182:183], v[236:237], v[152:153] op_sel_hi:[1,0]
	v_pk_fma_f32 v[180:181], v[238:239], v[164:165], v[180:181] op_sel:[0,1,0]
	v_pk_fma_f32 v[182:183], v[238:239], v[152:153], v[182:183] op_sel:[0,1,0]
	v_pk_fma_f32 v[180:181], v[240:241], v[166:167], v[180:181] op_sel_hi:[1,0,1]
	v_pk_fma_f32 v[182:183], v[240:241], v[154:155], v[182:183] op_sel_hi:[1,0,1]
	v_pk_fma_f32 v[180:181], v[242:243], v[166:167], v[180:181] op_sel:[0,1,0]
	v_pk_fma_f32 v[182:183], v[242:243], v[154:155], v[182:183] op_sel:[0,1,0]
	v_pk_mul_f32 v[186:187], v[158:159], v[172:173] op_sel_hi:[1,0]
	v_add_f32_dpp v184, v181, v180 row_ror:8 row_mask:0xf bank_mask:0xf
	v_pk_mul_f32 v[188:189], v[158:159], v[172:173] op_sel:[0,1]
	v_pk_mul_f32 v[190:191], v[158:159], v[174:175] op_sel_hi:[1,0]
	v_add_f32_dpp v184, v184, v184 quad_perm:[1,0,3,2] row_mask:0xf bank_mask:0xf
	v_pk_mul_f32 v[192:193], v[158:159], v[174:175] op_sel:[0,1]
	ds_read_b128 v[152:155], v195 offset:2176
	v_add_f32_dpp v184, v184, v184 quad_perm:[2,3,0,1] row_mask:0xf bank_mask:0xf
	v_pk_fma_f32 v[186:187], v[236:237], v[160:161], v[186:187] op_sel_hi:[1,0,1]
	v_pk_fma_f32 v[188:189], v[238:239], v[160:161], v[188:189] op_sel:[0,1,0]
	v_add_f32_dpp v184, v184, v184 row_half_mirror row_mask:0xf bank_mask:0xf
	v_pk_fma_f32 v[190:191], v[240:241], v[162:163], v[190:191] op_sel_hi:[1,0,1]
	v_pk_fma_f32 v[192:193], v[242:243], v[162:163], v[192:193] op_sel:[0,1,0]
	v_mov_b32_dpp v185, v184 row_ror:8 row_mask:0xf bank_mask:0xf
	ds_write_b64 v247, v[182:183] offset:3456
	v_pk_fma_f32 v[236:237], v[168:169], v[184:185], v[186:187] op_sel_hi:[0,1,1] neg_lo:[1,0,0] neg_hi:[1,0,0]
	v_pk_fma_f32 v[238:239], v[168:169], v[184:185], v[188:189] op_sel:[1,0,0] neg_lo:[1,0,0] neg_hi:[1,0,0]
	v_pk_fma_f32 v[240:241], v[170:171], v[184:185], v[190:191] op_sel_hi:[0,1,1] neg_lo:[1,0,0] neg_hi:[1,0,0]
	v_pk_fma_f32 v[242:243], v[170:171], v[184:185], v[192:193] op_sel:[1,0,0] neg_lo:[1,0,0] neg_hi:[1,0,0]
	ds_read_b128 v[164:167], v194 offset:19856
	ds_read_b64 v[158:159], v196 offset:2448
	ds_read_b128 v[172:175], v194 offset:54672
	ds_read_b128 v[160:163], v194 offset:2448
	ds_read_b128 v[168:171], v194 offset:37264
	s_waitcnt lgkmcnt(7)
; template <int CTRL> __device__ __forceinline__ float dppf(float x) { return __builtin_bit_cast(float, __builtin_amdgcn_update_dpp(0, __builtin_bit_cast(int, x), CTRL, 0xF, 0xF, false)); }
; __device__ __forceinline__ void phase_rwkv_scan(const Fr& F, int jr) {
;     ...
;                 for (int pg = 0; pg < 64; pg += 16) {
; #pragma unroll
;                     for (int pi = 0; pi < 16; ++pi) {
;                         const int p = pg + pi, pn = p < 63 ? p + 1 : 63;
;                         const f32x4 w4n = PW[pn * 16], k4n = PW[1024 + pn * 16], b4n = PW[2048 + pn * 16], d4n = PW[3072 + pn * 16], r4n = PR[pn * 16];
;                         const float vvn = PV[pn * 32];
;                         f32x2 t = S01 * k4.xy; t = S23 * k4.zw + t; float sa = t.x + t.y;
;                         sa += dppf<0x128>(sa);
;                         const f32x2 dv01 = d4.xy * vv, dv23 = d4.zw * vv;
;                         sa += dppf<0x124>(sa);
;                         const f32x2 e01 = S01 * w4.xy + dv01;
;                         sa += dppf<0x122>(sa);
;                         const f32x2 e23 = S23 * w4.zw + dv23;
;                         sa += dppf<0x121>(sa);
;                         S01 = e01 - b4.xy * sa; S23 = e23 - b4.zw * sa;
;                         f32x2 u = S01 * r4.xy; u = S23 * r4.zw + u;
;                         PY[pi * 64] = u.x + u.y;
;                         w4 = w4n; k4 = k4n; b4 = b4n; d4 = d4n; r4 = r4n; vv = vvn;
	v_pk_mul_f32 v[180:181], v[236:237], v[140:141] op_sel_hi:[1,0]
	v_pk_mul_f32 v[182:183], v[236:237], v[176:177] op_sel_hi:[1,0]
	v_pk_fma_f32 v[180:181], v[238:239], v[140:141], v[180:181] op_sel:[0,1,0]
	v_pk_fma_f32 v[182:183], v[238:239], v[176:177], v[182:183] op_sel:[0,1,0]
	v_pk_fma_f32 v[180:181], v[240:241], v[142:143], v[180:181] op_sel_hi:[1,0,1]
	v_pk_fma_f32 v[182:183], v[240:241], v[178:179], v[182:183] op_sel_hi:[1,0,1]
	v_pk_fma_f32 v[180:181], v[242:243], v[142:143], v[180:181] op_sel:[0,1,0]
	v_pk_fma_f32 v[182:183], v[242:243], v[178:179], v[182:183] op_sel:[0,1,0]
	v_pk_mul_f32 v[186:187], v[156:157], v[148:149] op_sel_hi:[1,0]
	v_add_f32_dpp v184, v181, v180 row_ror:8 row_mask:0xf bank_mask:0xf
	v_pk_mul_f32 v[188:189], v[156:157], v[148:149] op_sel:[0,1]
	v_pk_mul_f32 v[190:191], v[156:157], v[150:151] op_sel_hi:[1,0]
	v_add_f32_dpp v184, v184, v184 quad_perm:[1,0,3,2] row_mask:0xf bank_mask:0xf
	v_pk_mul_f32 v[192:193], v[156:157], v[150:151] op_sel:[0,1]
	ds_read_b128 v[176:179], v195 offset:2448
	v_add_f32_dpp v184, v184, v184 quad_perm:[2,3,0,1] row_mask:0xf bank_mask:0xf
	v_pk_fma_f32 v[186:187], v[236:237], v[136:137], v[186:187] op_sel_hi:[1,0,1]
	v_pk_fma_f32 v[188:189], v[238:239], v[136:137], v[188:189] op_sel:[0,1,0]
	v_add_f32_dpp v184, v184, v184 row_half_mirror row_mask:0xf bank_mask:0xf
	v_pk_fma_f32 v[190:191], v[240:241], v[138:139], v[190:191] op_sel_hi:[1,0,1]
	v_pk_fma_f32 v[192:193], v[242:243], v[138:139], v[192:193] op_sel:[0,1,0]
	v_mov_b32_dpp v185, v184 row_ror:8 row_mask:0xf bank_mask:0xf
	ds_write_b64 v247, v[182:183] offset:4032
	v_pk_fma_f32 v[236:237], v[144:145], v[184:185], v[186:187] op_sel_hi:[0,1,1] neg_lo:[1,0,0] neg_hi:[1,0,0]
	v_pk_fma_f32 v[238:239], v[144:145], v[184:185], v[188:189] op_sel:[1,0,0] neg_lo:[1,0,0] neg_hi:[1,0,0]
	v_pk_fma_f32 v[240:241], v[146:147], v[184:185], v[190:191] op_sel_hi:[0,1,1] neg_lo:[1,0,0] neg_hi:[1,0,0]
	v_pk_fma_f32 v[242:243], v[146:147], v[184:185], v[192:193] op_sel:[1,0,0] neg_lo:[1,0,0] neg_hi:[1,0,0]
	ds_read_b128 v[140:143], v194 offset:20128
	ds_read_b64 v[156:157], v196 offset:2720
	ds_read_b128 v[148:151], v194 offset:54944
	ds_read_b128 v[136:139], v194 offset:2720
	ds_read_b128 v[144:147], v194 offset:37536
	s_waitcnt lgkmcnt(7)
	v_pk_mul_f32 v[180:181], v[236:237], v[164:165] op_sel_hi:[1,0]
	v_pk_mul_f32 v[182:183], v[236:237], v[152:153] op_sel_hi:[1,0]
	v_pk_fma_f32 v[180:181], v[238:239], v[164:165], v[180:181] op_sel:[0,1,0]
	v_pk_fma_f32 v[182:183], v[238:239], v[152:153], v[182:183] op_sel:[0,1,0]
	v_pk_fma_f32 v[180:181], v[240:241], v[166:167], v[180:181] op_sel_hi:[1,0,1]
	v_pk_fma_f32 v[182:183], v[240:241], v[154:155], v[182:183] op_sel_hi:[1,0,1]
	v_pk_fma_f32 v[180:181], v[242:243], v[166:167], v[180:181] op_sel:[0,1,0]
	v_pk_fma_f32 v[182:183], v[242:243], v[154:155], v[182:183] op_sel:[0,1,0]
	v_pk_mul_f32 v[186:187], v[158:159], v[172:173] op_sel_hi:[1,0]
	v_add_f32_dpp v184, v181, v180 row_ror:8 row_mask:0xf bank_mask:0xf
	v_pk_mul_f32 v[188:189], v[158:159], v[172:173] op_sel:[0,1]
	v_pk_mul_f32 v[190:191], v[158:159], v[174:175] op_sel_hi:[1,0]
	v_add_f32_dpp v184, v184, v184 quad_perm:[1,0,3,2] row_mask:0xf bank_mask:0xf
	v_pk_mul_f32 v[192:193], v[158:159], v[174:175] op_sel:[0,1]
	ds_read_b128 v[152:155], v195 offset:2720
	v_add_f32_dpp v184, v184, v184 quad_perm:[2,3,0,1] row_mask:0xf bank_mask:0xf
	v_pk_fma_f32 v[186:187], v[236:237], v[160:161], v[186:187] op_sel_hi:[1,0,1]
	v_pk_fma_f32 v[188:189], v[238:239], v[160:161], v[188:189] op_sel:[0,1,0]
	v_add_f32_dpp v184, v184, v184 row_half_mirror row_mask:0xf bank_mask:0xf
	v_pk_fma_f32 v[190:191], v[240:241], v[162:163], v[190:191] op_sel_hi:[1,0,1]
	v_pk_fma_f32 v[192:193], v[242:243], v[162:163], v[192:193] op_sel:[0,1,0]
	v_mov_b32_dpp v185, v184 row_ror:8 row_mask:0xf bank_mask:0xf
	ds_write_b64 v247, v[182:183] offset:4608
	v_pk_fma_f32 v[236:237], v[168:169], v[184:185], v[186:187] op_sel_hi:[0,1,1] neg_lo:[1,0,0] neg_hi:[1,0,0]
	v_pk_fma_f32 v[238:239], v[168:169], v[184:185], v[188:189] op_sel:[1,0,0] neg_lo:[1,0,0] neg_hi:[1,0,0]
	v_pk_fma_f32 v[240:241], v[170:171], v[184:185], v[190:191] op_sel_hi:[0,1,1] neg_lo:[1,0,0] neg_hi:[1,0,0]
	v_pk_fma_f32 v[242:243], v[170:171], v[184:185], v[192:193] op_sel:[1,0,0] neg_lo:[1,0,0] neg_hi:[1,0,0]
	ds_read_b128 v[164:167], v194 offset:20400
	ds_read_b64 v[158:159], v196 offset:2992
	ds_read_b128 v[172:175], v194 offset:55216
	ds_read_b128 v[160:163], v194 offset:2992
	ds_read_b128 v[168:171], v194 offset:37808
	s_waitcnt lgkmcnt(7)
; template <int CTRL> __device__ __forceinline__ float dppf(float x) { return __builtin_bit_cast(float, __builtin_amdgcn_update_dpp(0, __builtin_bit_cast(int, x), CTRL, 0xF, 0xF, false)); }
; __device__ __forceinline__ void phase_rwkv_scan(const Fr& F, int jr) {
;     ...
;                 for (int pg = 0; pg < 64; pg += 16) {
; #pragma unroll
;                     for (int pi = 0; pi < 16; ++pi) {
;                         const int p = pg + pi, pn = p < 63 ? p + 1 : 63;
;                         const f32x4 w4n = PW[pn * 16], k4n = PW[1024 + pn * 16], b4n = PW[2048 + pn * 16], d4n = PW[3072 + pn * 16], r4n = PR[pn * 16];
;                         const float vvn = PV[pn * 32];
;                         f32x2 t = S01 * k4.xy; t = S23 * k4.zw + t; float sa = t.x + t.y;
;                         sa += dppf<0x128>(sa);
;                         const f32x2 dv01 = d4.xy * vv, dv23 = d4.zw * vv;
;                         sa += dppf<0x124>(sa);
;                         const f32x2 e01 = S01 * w4.xy + dv01;
;                         sa += dppf<0x122>(sa);
;                         const f32x2 e23 = S23 * w4.zw + dv23;
;                         sa += dppf<0x121>(sa);
;                         S01 = e01 - b4.xy * sa; S23 = e23 - b4.zw * sa;
;                         f32x2 u = S01 * r4.xy; u = S23 * r4.zw + u;
;                         PY[pi * 64] = u.x + u.y;
;                         w4 = w4n; k4 = k4n; b4 = b4n; d4 = d4n; r4 = r4n; vv = vvn;
	v_pk_mul_f32 v[180:181], v[236:237], v[140:141] op_sel_hi:[1,0]
	v_pk_mul_f32 v[182:183], v[236:237], v[176:177] op_sel_hi:[1,0]
	v_pk_fma_f32 v[180:181], v[238:239], v[140:141], v[180:181] op_sel:[0,1,0]
	v_pk_fma_f32 v[182:183], v[238:239], v[176:177], v[182:183] op_sel:[0,1,0]
	v_pk_fma_f32 v[180:181], v[240:241], v[142:143], v[180:181] op_sel_hi:[1,0,1]
	v_pk_fma_f32 v[182:183], v[240:241], v[178:179], v[182:183] op_sel_hi:[1,0,1]
	v_pk_fma_f32 v[180:181], v[242:243], v[142:143], v[180:181] op_sel:[0,1,0]
	v_pk_fma_f32 v[182:183], v[242:243], v[178:179], v[182:183] op_sel:[0,1,0]
	v_pk_mul_f32 v[186:187], v[156:157], v[148:149] op_sel_hi:[1,0]
	v_add_f32_dpp v184, v181, v180 row_ror:8 row_mask:0xf bank_mask:0xf
	v_pk_mul_f32 v[188:189], v[156:157], v[148:149] op_sel:[0,1]
	v_pk_mul_f32 v[190:191], v[156:157], v[150:151] op_sel_hi:[1,0]
	v_add_f32_dpp v184, v184, v184 quad_perm:[1,0,3,2] row_mask:0xf bank_mask:0xf
	v_pk_mul_f32 v[192:193], v[156:157], v[150:151] op_sel:[0,1]
	ds_read_b128 v[176:179], v195 offset:2992
	v_add_f32_dpp v184, v184, v184 quad_perm:[2,3,0,1] row_mask:0xf bank_mask:0xf
	v_pk_fma_f32 v[186:187], v[236:237], v[136:137], v[186:187] op_sel_hi:[1,0,1]
	v_pk_fma_f32 v[188:189], v[238:239], v[136:137], v[188:189] op_sel:[0,1,0]
	v_add_f32_dpp v184, v184, v184 row_half_mirror row_mask:0xf bank_mask:0xf
	v_pk_fma_f32 v[190:191], v[240:241], v[138:139], v[190:191] op_sel_hi:[1,0,1]
	v_pk_fma_f32 v[192:193], v[242:243], v[138:139], v[192:193] op_sel:[0,1,0]
	v_mov_b32_dpp v185, v184 row_ror:8 row_mask:0xf bank_mask:0xf
	ds_write_b64 v247, v[182:183] offset:5184
	v_pk_fma_f32 v[236:237], v[144:145], v[184:185], v[186:187] op_sel_hi:[0,1,1] neg_lo:[1,0,0] neg_hi:[1,0,0]
	v_pk_fma_f32 v[238:239], v[144:145], v[184:185], v[188:189] op_sel:[1,0,0] neg_lo:[1,0,0] neg_hi:[1,0,0]
	v_pk_fma_f32 v[240:241], v[146:147], v[184:185], v[190:191] op_sel_hi:[0,1,1] neg_lo:[1,0,0] neg_hi:[1,0,0]
	v_pk_fma_f32 v[242:243], v[146:147], v[184:185], v[192:193] op_sel:[1,0,0] neg_lo:[1,0,0] neg_hi:[1,0,0]
	ds_read_b128 v[140:143], v194 offset:20672
	ds_read_b64 v[156:157], v196 offset:3264
	ds_read_b128 v[148:151], v194 offset:55488
	ds_read_b128 v[136:139], v194 offset:3264
	ds_read_b128 v[144:147], v194 offset:38080
	s_waitcnt lgkmcnt(7)
	v_pk_mul_f32 v[180:181], v[236:237], v[164:165] op_sel_hi:[1,0]
	v_pk_mul_f32 v[182:183], v[236:237], v[152:153] op_sel_hi:[1,0]
	v_pk_fma_f32 v[180:181], v[238:239], v[164:165], v[180:181] op_sel:[0,1,0]
	v_pk_fma_f32 v[182:183], v[238:239], v[152:153], v[182:183] op_sel:[0,1,0]
	v_pk_fma_f32 v[180:181], v[240:241], v[166:167], v[180:181] op_sel_hi:[1,0,1]
	v_pk_fma_f32 v[182:183], v[240:241], v[154:155], v[182:183] op_sel_hi:[1,0,1]
	v_pk_fma_f32 v[180:181], v[242:243], v[166:167], v[180:181] op_sel:[0,1,0]
	v_pk_fma_f32 v[182:183], v[242:243], v[154:155], v[182:183] op_sel:[0,1,0]
	v_pk_mul_f32 v[186:187], v[158:159], v[172:173] op_sel_hi:[1,0]
	v_add_f32_dpp v184, v181, v180 row_ror:8 row_mask:0xf bank_mask:0xf
	v_pk_mul_f32 v[188:189], v[158:159], v[172:173] op_sel:[0,1]
	v_pk_mul_f32 v[190:191], v[158:159], v[174:175] op_sel_hi:[1,0]
	v_add_f32_dpp v184, v184, v184 quad_perm:[1,0,3,2] row_mask:0xf bank_mask:0xf
	v_pk_mul_f32 v[192:193], v[158:159], v[174:175] op_sel:[0,1]
	ds_read_b128 v[152:155], v195 offset:3264
	v_add_f32_dpp v184, v184, v184 quad_perm:[2,3,0,1] row_mask:0xf bank_mask:0xf
	v_pk_fma_f32 v[186:187], v[236:237], v[160:161], v[186:187] op_sel_hi:[1,0,1]
	v_pk_fma_f32 v[188:189], v[238:239], v[160:161], v[188:189] op_sel:[0,1,0]
	v_add_f32_dpp v184, v184, v184 row_half_mirror row_mask:0xf bank_mask:0xf
	v_pk_fma_f32 v[190:191], v[240:241], v[162:163], v[190:191] op_sel_hi:[1,0,1]
	v_pk_fma_f32 v[192:193], v[242:243], v[162:163], v[192:193] op_sel:[0,1,0]
	v_mov_b32_dpp v185, v184 row_ror:8 row_mask:0xf bank_mask:0xf
	ds_write_b64 v247, v[182:183] offset:5760
	v_pk_fma_f32 v[236:237], v[168:169], v[184:185], v[186:187] op_sel_hi:[0,1,1] neg_lo:[1,0,0] neg_hi:[1,0,0]
	v_pk_fma_f32 v[238:239], v[168:169], v[184:185], v[188:189] op_sel:[1,0,0] neg_lo:[1,0,0] neg_hi:[1,0,0]
	v_pk_fma_f32 v[240:241], v[170:171], v[184:185], v[190:191] op_sel_hi:[0,1,1] neg_lo:[1,0,0] neg_hi:[1,0,0]
	v_pk_fma_f32 v[242:243], v[170:171], v[184:185], v[192:193] op_sel:[1,0,0] neg_lo:[1,0,0] neg_hi:[1,0,0]
	ds_read_b128 v[164:167], v194 offset:20944
	ds_read_b64 v[158:159], v196 offset:3536
	ds_read_b128 v[172:175], v194 offset:55760
	ds_read_b128 v[160:163], v194 offset:3536
	ds_read_b128 v[168:171], v194 offset:38352
	s_waitcnt lgkmcnt(7)
; template <int CTRL> __device__ __forceinline__ float dppf(float x) { return __builtin_bit_cast(float, __builtin_amdgcn_update_dpp(0, __builtin_bit_cast(int, x), CTRL, 0xF, 0xF, false)); }
; __device__ __forceinline__ void phase_rwkv_scan(const Fr& F, int jr) {
;     ...
;                 for (int pg = 0; pg < 64; pg += 16) {
; #pragma unroll
;                     for (int pi = 0; pi < 16; ++pi) {
;                         const int p = pg + pi, pn = p < 63 ? p + 1 : 63;
;                         const f32x4 w4n = PW[pn * 16], k4n = PW[1024 + pn * 16], b4n = PW[2048 + pn * 16], d4n = PW[3072 + pn * 16], r4n = PR[pn * 16];
;                         const float vvn = PV[pn * 32];
;                         f32x2 t = S01 * k4.xy; t = S23 * k4.zw + t; float sa = t.x + t.y;
;                         sa += dppf<0x128>(sa);
;                         const f32x2 dv01 = d4.xy * vv, dv23 = d4.zw * vv;
;                         sa += dppf<0x124>(sa);
;                         const f32x2 e01 = S01 * w4.xy + dv01;
;                         sa += dppf<0x122>(sa);
;                         const f32x2 e23 = S23 * w4.zw + dv23;
;                         sa += dppf<0x121>(sa);
;                         S01 = e01 - b4.xy * sa; S23 = e23 - b4.zw * sa;
;                         f32x2 u = S01 * r4.xy; u = S23 * r4.zw + u;
;                         PY[pi * 64] = u.x + u.y;
;                         w4 = w4n; k4 = k4n; b4 = b4n; d4 = d4n; r4 = r4n; vv = vvn;
	v_pk_mul_f32 v[180:181], v[236:237], v[140:141] op_sel_hi:[1,0]
	v_pk_mul_f32 v[182:183], v[236:237], v[176:177] op_sel_hi:[1,0]
	v_pk_fma_f32 v[180:181], v[238:239], v[140:141], v[180:181] op_sel:[0,1,0]
	v_pk_fma_f32 v[182:183], v[238:239], v[176:177], v[182:183] op_sel:[0,1,0]
	v_pk_fma_f32 v[180:181], v[240:241], v[142:143], v[180:181] op_sel_hi:[1,0,1]
	v_pk_fma_f32 v[182:183], v[240:241], v[178:179], v[182:183] op_sel_hi:[1,0,1]
	v_pk_fma_f32 v[180:181], v[242:243], v[142:143], v[180:181] op_sel:[0,1,0]
	v_pk_fma_f32 v[182:183], v[242:243], v[178:179], v[182:183] op_sel:[0,1,0]
	v_pk_mul_f32 v[186:187], v[156:157], v[148:149] op_sel_hi:[1,0]
	v_add_f32_dpp v184, v181, v180 row_ror:8 row_mask:0xf bank_mask:0xf
	v_pk_mul_f32 v[188:189], v[156:157], v[148:149] op_sel:[0,1]
	v_pk_mul_f32 v[190:191], v[156:157], v[150:151] op_sel_hi:[1,0]
	v_add_f32_dpp v184, v184, v184 quad_perm:[1,0,3,2] row_mask:0xf bank_mask:0xf
	v_pk_mul_f32 v[192:193], v[156:157], v[150:151] op_sel:[0,1]
	ds_read_b128 v[176:179], v195 offset:3536
	v_add_f32_dpp v184, v184, v184 quad_perm:[2,3,0,1] row_mask:0xf bank_mask:0xf
	v_pk_fma_f32 v[186:187], v[236:237], v[136:137], v[186:187] op_sel_hi:[1,0,1]
	v_pk_fma_f32 v[188:189], v[238:239], v[136:137], v[188:189] op_sel:[0,1,0]
	v_add_f32_dpp v184, v184, v184 row_half_mirror row_mask:0xf bank_mask:0xf
	v_pk_fma_f32 v[190:191], v[240:241], v[138:139], v[190:191] op_sel_hi:[1,0,1]
	v_pk_fma_f32 v[192:193], v[242:243], v[138:139], v[192:193] op_sel:[0,1,0]
	v_mov_b32_dpp v185, v184 row_ror:8 row_mask:0xf bank_mask:0xf
	ds_write_b64 v247, v[182:183] offset:6336
	v_pk_fma_f32 v[236:237], v[144:145], v[184:185], v[186:187] op_sel_hi:[0,1,1] neg_lo:[1,0,0] neg_hi:[1,0,0]
	v_pk_fma_f32 v[238:239], v[144:145], v[184:185], v[188:189] op_sel:[1,0,0] neg_lo:[1,0,0] neg_hi:[1,0,0]
	v_pk_fma_f32 v[240:241], v[146:147], v[184:185], v[190:191] op_sel_hi:[0,1,1] neg_lo:[1,0,0] neg_hi:[1,0,0]
	v_pk_fma_f32 v[242:243], v[146:147], v[184:185], v[192:193] op_sel:[1,0,0] neg_lo:[1,0,0] neg_hi:[1,0,0]
	ds_read_b128 v[140:143], v194 offset:21216
	ds_read_b64 v[156:157], v196 offset:3808
	ds_read_b128 v[148:151], v194 offset:56032
	ds_read_b128 v[136:139], v194 offset:3808
	ds_read_b128 v[144:147], v194 offset:38624
	s_waitcnt lgkmcnt(7)
	v_pk_mul_f32 v[180:181], v[236:237], v[164:165] op_sel_hi:[1,0]
	v_pk_mul_f32 v[182:183], v[236:237], v[152:153] op_sel_hi:[1,0]
	v_pk_fma_f32 v[180:181], v[238:239], v[164:165], v[180:181] op_sel:[0,1,0]
	v_pk_fma_f32 v[182:183], v[238:239], v[152:153], v[182:183] op_sel:[0,1,0]
	v_pk_fma_f32 v[180:181], v[240:241], v[166:167], v[180:181] op_sel_hi:[1,0,1]
	v_pk_fma_f32 v[182:183], v[240:241], v[154:155], v[182:183] op_sel_hi:[1,0,1]
	v_pk_fma_f32 v[180:181], v[242:243], v[166:167], v[180:181] op_sel:[0,1,0]
	v_pk_fma_f32 v[182:183], v[242:243], v[154:155], v[182:183] op_sel:[0,1,0]
	v_pk_mul_f32 v[186:187], v[158:159], v[172:173] op_sel_hi:[1,0]
	v_add_f32_dpp v184, v181, v180 row_ror:8 row_mask:0xf bank_mask:0xf
	v_pk_mul_f32 v[188:189], v[158:159], v[172:173] op_sel:[0,1]
	v_pk_mul_f32 v[190:191], v[158:159], v[174:175] op_sel_hi:[1,0]
	v_add_f32_dpp v184, v184, v184 quad_perm:[1,0,3,2] row_mask:0xf bank_mask:0xf
	v_pk_mul_f32 v[192:193], v[158:159], v[174:175] op_sel:[0,1]
	ds_read_b128 v[152:155], v195 offset:3808
	v_add_f32_dpp v184, v184, v184 quad_perm:[2,3,0,1] row_mask:0xf bank_mask:0xf
	v_pk_fma_f32 v[186:187], v[236:237], v[160:161], v[186:187] op_sel_hi:[1,0,1]
	v_pk_fma_f32 v[188:189], v[238:239], v[160:161], v[188:189] op_sel:[0,1,0]
	v_add_f32_dpp v184, v184, v184 row_half_mirror row_mask:0xf bank_mask:0xf
	v_pk_fma_f32 v[190:191], v[240:241], v[162:163], v[190:191] op_sel_hi:[1,0,1]
	v_pk_fma_f32 v[192:193], v[242:243], v[162:163], v[192:193] op_sel:[0,1,0]
	v_mov_b32_dpp v185, v184 row_ror:8 row_mask:0xf bank_mask:0xf
	ds_write_b64 v247, v[182:183] offset:6912
	v_pk_fma_f32 v[236:237], v[168:169], v[184:185], v[186:187] op_sel_hi:[0,1,1] neg_lo:[1,0,0] neg_hi:[1,0,0]
	v_pk_fma_f32 v[238:239], v[168:169], v[184:185], v[188:189] op_sel:[1,0,0] neg_lo:[1,0,0] neg_hi:[1,0,0]
	v_pk_fma_f32 v[240:241], v[170:171], v[184:185], v[190:191] op_sel_hi:[0,1,1] neg_lo:[1,0,0] neg_hi:[1,0,0]
	v_pk_fma_f32 v[242:243], v[170:171], v[184:185], v[192:193] op_sel:[1,0,0] neg_lo:[1,0,0] neg_hi:[1,0,0]
	ds_read_b128 v[164:167], v194 offset:21488
	ds_read_b64 v[158:159], v196 offset:4080
	ds_read_b128 v[172:175], v194 offset:56304
	ds_read_b128 v[160:163], v194 offset:4080
	ds_read_b128 v[168:171], v194 offset:38896
	s_waitcnt lgkmcnt(7)
; __device__ __forceinline__ unsigned f2bf(float f) { unsigned u = __builtin_bit_cast(unsigned, f); return (u + 0x7fffu + ((u >> 16) & 1u)) >> 16; }
; __device__ __forceinline__ void phase_rwkv_scan(const Fr& F, int jr) {
;     ...
;             if (chunk + 1 < TB / 64) {
;                 const size_t row1 = (size_t)b * TB + tokof(s, (chunk + 1) * 64 + p1), row2 = (size_t)b * TB + tokof(s, (chunk + 1) * 64 + p2);
; #pragma unroll
;     ...
;                 for (int pg = 0; pg < 64; pg += 16) {
; #pragma unroll
;                     for (int pi = 0; pi < 16; ++pi) {
;                         const int p = pg + pi, pn = p < 63 ? p + 1 : 63;
;                         const f32x4 w4n = PW[pn * 16], k4n = PW[1024 + pn * 16], b4n = PW[2048 + pn * 16], d4n = PW[3072 + pn * 16], r4n = PR[pn * 16];
;                         const float vvn = PV[pn * 32];
;                         f32x2 t = S01 * k4.xy; t = S23 * k4.zw + t; float sa = t.x + t.y;
;                         sa += dppf<0x128>(sa);
;                         const f32x2 dv01 = d4.xy * vv, dv23 = d4.zw * vv;
;                         sa += dppf<0x124>(sa);
;                         const f32x2 e01 = S01 * w4.xy + dv01;
;                         sa += dppf<0x122>(sa);
;                         const f32x2 e23 = S23 * w4.zw + dv23;
;                         sa += dppf<0x121>(sa);
;                         S01 = e01 - b4.xy * sa; S23 = e23 - b4.zw * sa;
;                         f32x2 u = S01 * r4.xy; u = S23 * r4.zw + u;
;                         PY[pi * 64] = u.x + u.y;
;                         w4 = w4n; k4 = k4n; b4 = b4n; d4 = d4n; r4 = r4n; vv = vvn;
;                     }
;                     asm volatile("s_waitcnt lgkmcnt(0)" ::: "memory");
;                     {
;                         const int j = lane >> 2, q = lane & 3; const float* yp = Ypw + j * 64 + q * 16;
;                         const f32x4 a0 = *(const f32x4*)yp, a1 = *(const f32x4*)(yp + 4), a2 = *(const f32x4*)(yp + 8), a3 = *(const f32x4*)(yp + 12);
;                         const f32x4 ssum = (a0 + a1) + (a2 + a3); const float yv = (ssum.x + ssum.y) + (ssum.z + ssum.w);
;                         const size_t row = (size_t)b * TB + tokof(s, chunk * 64 + pg + j);
;                         Yb[row * D + h * 64 + 32 * half + 4 * wave + q] = (bf16)f2bf(yv);
;                     }
;                     asm volatile("s_waitcnt lgkmcnt(0)" ::: "memory");
	v_pk_mul_f32 v[180:181], v[236:237], v[140:141] op_sel_hi:[1,0]
	v_pk_mul_f32 v[182:183], v[236:237], v[176:177] op_sel_hi:[1,0]
	v_pk_fma_f32 v[180:181], v[238:239], v[140:141], v[180:181] op_sel:[0,1,0]
	v_pk_fma_f32 v[182:183], v[238:239], v[176:177], v[182:183] op_sel:[0,1,0]
	v_pk_fma_f32 v[180:181], v[240:241], v[142:143], v[180:181] op_sel_hi:[1,0,1]
	v_pk_fma_f32 v[182:183], v[240:241], v[178:179], v[182:183] op_sel_hi:[1,0,1]
	v_pk_fma_f32 v[180:181], v[242:243], v[142:143], v[180:181] op_sel:[0,1,0]
	v_pk_fma_f32 v[182:183], v[242:243], v[178:179], v[182:183] op_sel:[0,1,0]
	v_pk_mul_f32 v[186:187], v[156:157], v[148:149] op_sel_hi:[1,0]
	v_add_f32_dpp v184, v181, v180 row_ror:8 row_mask:0xf bank_mask:0xf
	v_pk_mul_f32 v[188:189], v[156:157], v[148:149] op_sel:[0,1]
	v_pk_mul_f32 v[190:191], v[156:157], v[150:151] op_sel_hi:[1,0]
	v_add_f32_dpp v184, v184, v184 quad_perm:[1,0,3,2] row_mask:0xf bank_mask:0xf
	v_pk_mul_f32 v[192:193], v[156:157], v[150:151] op_sel:[0,1]
	ds_read_b128 v[176:179], v195 offset:4080
	v_add_f32_dpp v184, v184, v184 quad_perm:[2,3,0,1] row_mask:0xf bank_mask:0xf
	v_pk_fma_f32 v[186:187], v[236:237], v[136:137], v[186:187] op_sel_hi:[1,0,1]
	v_pk_fma_f32 v[188:189], v[238:239], v[136:137], v[188:189] op_sel:[0,1,0]
	v_add_f32_dpp v184, v184, v184 row_half_mirror row_mask:0xf bank_mask:0xf
	v_pk_fma_f32 v[190:191], v[240:241], v[138:139], v[190:191] op_sel_hi:[1,0,1]
	v_pk_fma_f32 v[192:193], v[242:243], v[138:139], v[192:193] op_sel:[0,1,0]
	v_mov_b32_dpp v185, v184 row_ror:8 row_mask:0xf bank_mask:0xf
	ds_write_b64 v247, v[182:183] offset:7488
	v_pk_fma_f32 v[236:237], v[144:145], v[184:185], v[186:187] op_sel_hi:[0,1,1] neg_lo:[1,0,0] neg_hi:[1,0,0]
	v_pk_fma_f32 v[238:239], v[144:145], v[184:185], v[188:189] op_sel:[1,0,0] neg_lo:[1,0,0] neg_hi:[1,0,0]
	v_pk_fma_f32 v[240:241], v[146:147], v[184:185], v[190:191] op_sel_hi:[0,1,1] neg_lo:[1,0,0] neg_hi:[1,0,0]
	v_pk_fma_f32 v[242:243], v[146:147], v[184:185], v[192:193] op_sel:[1,0,0] neg_lo:[1,0,0] neg_hi:[1,0,0]
	ds_read_b128 v[140:143], v194 offset:21760
	ds_read_b64 v[156:157], v196 offset:4352
	ds_read_b128 v[148:151], v194 offset:56576
	ds_read_b128 v[136:139], v194 offset:4352
	ds_read_b128 v[144:147], v194 offset:39168
	s_waitcnt lgkmcnt(7)
	v_pk_mul_f32 v[180:181], v[236:237], v[164:165] op_sel_hi:[1,0]
	v_pk_mul_f32 v[182:183], v[236:237], v[152:153] op_sel_hi:[1,0]
	v_pk_fma_f32 v[180:181], v[238:239], v[164:165], v[180:181] op_sel:[0,1,0]
	v_pk_fma_f32 v[182:183], v[238:239], v[152:153], v[182:183] op_sel:[0,1,0]
	v_pk_fma_f32 v[180:181], v[240:241], v[166:167], v[180:181] op_sel_hi:[1,0,1]
	v_pk_fma_f32 v[182:183], v[240:241], v[154:155], v[182:183] op_sel_hi:[1,0,1]
	v_pk_fma_f32 v[180:181], v[242:243], v[166:167], v[180:181] op_sel:[0,1,0]
	v_pk_fma_f32 v[182:183], v[242:243], v[154:155], v[182:183] op_sel:[0,1,0]
	v_pk_mul_f32 v[186:187], v[158:159], v[172:173] op_sel_hi:[1,0]
	v_add_f32_dpp v184, v181, v180 row_ror:8 row_mask:0xf bank_mask:0xf
	v_pk_mul_f32 v[188:189], v[158:159], v[172:173] op_sel:[0,1]
	v_pk_mul_f32 v[190:191], v[158:159], v[174:175] op_sel_hi:[1,0]
	v_add_f32_dpp v184, v184, v184 quad_perm:[1,0,3,2] row_mask:0xf bank_mask:0xf
	v_pk_mul_f32 v[192:193], v[158:159], v[174:175] op_sel:[0,1]
	ds_read_b128 v[152:155], v195 offset:4352
	v_add_f32_dpp v184, v184, v184 quad_perm:[2,3,0,1] row_mask:0xf bank_mask:0xf
	v_pk_fma_f32 v[186:187], v[236:237], v[160:161], v[186:187] op_sel_hi:[1,0,1]
	v_pk_fma_f32 v[188:189], v[238:239], v[160:161], v[188:189] op_sel:[0,1,0]
	v_add_f32_dpp v184, v184, v184 row_half_mirror row_mask:0xf bank_mask:0xf
	v_pk_fma_f32 v[190:191], v[240:241], v[162:163], v[190:191] op_sel_hi:[1,0,1]
	v_pk_fma_f32 v[192:193], v[242:243], v[162:163], v[192:193] op_sel:[0,1,0]
	v_mov_b32_dpp v185, v184 row_ror:8 row_mask:0xf bank_mask:0xf
	ds_write_b64 v247, v[182:183] offset:8064
	v_pk_fma_f32 v[236:237], v[168:169], v[184:185], v[186:187] op_sel_hi:[0,1,1] neg_lo:[1,0,0] neg_hi:[1,0,0]
	v_pk_fma_f32 v[238:239], v[168:169], v[184:185], v[188:189] op_sel:[1,0,0] neg_lo:[1,0,0] neg_hi:[1,0,0]
	v_pk_fma_f32 v[240:241], v[170:171], v[184:185], v[190:191] op_sel_hi:[0,1,1] neg_lo:[1,0,0] neg_hi:[1,0,0]
	v_pk_fma_f32 v[242:243], v[170:171], v[184:185], v[192:193] op_sel:[1,0,0] neg_lo:[1,0,0] neg_hi:[1,0,0]
	s_waitcnt lgkmcnt(8)
	v_pk_mul_f32 v[182:183], v[236:237], v[176:177] op_sel_hi:[1,0]
	v_add_u32_e32 v197, s90, v249
	v_pk_fma_f32 v[182:183], v[238:239], v[176:177], v[182:183] op_sel:[0,1,0]
	v_lshl_add_u32 v197, v197, 11, v250
	v_pk_fma_f32 v[182:183], v[240:241], v[178:179], v[182:183] op_sel_hi:[1,0,1]
	v_add_u32_e32 v194, 0x1100, v194
	v_pk_fma_f32 v[182:183], v[242:243], v[178:179], v[182:183] op_sel:[0,1,0]
	v_add_u32_e32 v195, 0x1100, v195
	v_add_u32_e32 v196, 0x1100, v196
	s_waitcnt lgkmcnt(1)
	ds_write_b64 v247, v[182:183] offset:8640
	ds_read_b128 v[160:163], v248 offset:0
	ds_read_b128 v[164:167], v248 offset:16
	ds_read_b128 v[168:171], v248 offset:32
	ds_read_b128 v[172:175], v248 offset:48
	ds_read_b128 v[176:179], v248 offset:64
	ds_read_b128 v[186:189], v248 offset:80
	ds_read_b128 v[190:193], v248 offset:96
	ds_read_b128 v[180:183], v248 offset:112
	s_waitcnt lgkmcnt(6)
	v_pk_add_f32 v[160:161], v[160:161], v[162:163]
	v_pk_add_f32 v[164:165], v[164:165], v[166:167]
	s_waitcnt lgkmcnt(4)
	v_pk_add_f32 v[168:169], v[168:169], v[170:171]
	v_pk_add_f32 v[172:173], v[172:173], v[174:175]
	v_pk_add_f32 v[160:161], v[160:161], v[164:165]
	s_waitcnt lgkmcnt(2)
	v_pk_add_f32 v[176:177], v[176:177], v[178:179]
	v_pk_add_f32 v[186:187], v[186:187], v[188:189]
	v_pk_add_f32 v[168:169], v[168:169], v[172:173]
	s_waitcnt lgkmcnt(0)
	v_pk_add_f32 v[190:191], v[190:191], v[192:193]
	v_pk_add_f32 v[180:181], v[180:181], v[182:183]
	v_pk_add_f32 v[176:177], v[176:177], v[186:187]
	v_pk_add_f32 v[160:161], v[160:161], v[168:169]
	v_pk_add_f32 v[190:191], v[190:191], v[180:181]
	s_add_i32 s87, s87, 1
	v_pk_add_f32 v[176:177], v[176:177], v[190:191]
	s_add_i32 s90, s90, s94
	v_pk_add_f32 v[160:161], v[160:161], v[176:177] op_sel:[0,1] op_sel_hi:[1,0]
	s_cmp_lt_u32 s87, 4
	v_cvt_pk_bf16_f32 v198, v160, v161
	s_nop 0
	global_store_dword v197, v198, s[88:89]
	s_cmp_eq_u32 s87, 1
	s_cbranch_scc1 .Lrw0_bl0
	s_cmp_eq_u32 s87, 2
	s_cbranch_scc1 .Lrw0_bl1
	s_cmp_eq_u32 s87, 3
	s_cbranch_scc0 .Lrw0_bld
	global_load_dwordx2 v[112:113], v227, s[24:25] offset:0
	global_load_dwordx2 v[114:115], v227, s[24:25] offset:32
	global_load_dwordx2 v[120:121], v229, s[42:43]
	s_and_b32 s17, s10, s32
	s_xor_b32 s17, s17, s32
	s_cmp_eq_u32 s17, 0
	s_cbranch_scc1 .Lrw0_hnrb2
	global_load_dwordx2 v[116:117], v228, s[24:25] offset:0
	global_load_dwordx2 v[118:119], v228, s[24:25] offset:32

; #define LDS_BAR() asm volatile("s_waitcnt lgkmcnt(0)\n\ts_barrier" ::: "memory")
; __device__ __forceinline__ void phase_rwkv_scan(const Fr& F, int jr) {
;     ...
;             if (chunk + 1 < TB / 64) {
;                 const size_t row1 = (size_t)b * TB + tokof(s, (chunk + 1) * 64 + p1), row2 = (size_t)b * TB + tokof(s, (chunk + 1) * 64 + p2);
; #pragma unroll
;                 for (int kst = 0; kst < 2; ++kst) { Aw[kst] = *(const bf16x8*)(LM + row1 * 256 + 64 * s + 32 * kst + 8 * lq); Aa[kst] = *(const bf16x8*)(LM + row1 * 256 + 128 + 64 * s + 32 * kst + 8 * lq); }
;                 kw = *(const u32x4*)(Kb + row2 * D + h * 64 + hk0); rw = *(const u32x4*)(Rb + row2 * D + h * 64 + hk0); vw = *(const u32x2*)(Vb + row2 * D + h * 64 + 32 * half + 4 * j8);
;             }
;     ...
;             LDS_BAR();
;         }
.Lrw0_bl0:
	global_load_dwordx4 v[88:91], v226, s[20:21]
	global_load_dwordx4 v[92:95], v226, s[20:21] offset:64
	global_load_dwordx4 v[96:99], v226, s[20:21] offset:256
	global_load_dwordx4 v[100:103], v226, s[20:21] offset:320
	s_branch .Lrw0_bld
.Lrw0_bl1:
	global_load_dwordx2 v[104:105], v227, s[22:23] offset:0
	global_load_dwordx2 v[106:107], v227, s[22:23] offset:32
	global_load_dwordx2 v[108:109], v228, s[22:23] offset:0
	global_load_dwordx2 v[110:111], v228, s[22:23] offset:32
.Lrw0_bld:
	s_cmp_lt_u32 s87, 4
	s_waitcnt lgkmcnt(0)
	s_cbranch_scc1 .Lrw0_group
	s_branch .Lrw0_b2
.Lrw0_skip:
	global_load_dwordx4 v[88:91], v226, s[20:21]
	global_load_dwordx4 v[92:95], v226, s[20:21] offset:64
	global_load_dwordx4 v[96:99], v226, s[20:21] offset:256
	global_load_dwordx4 v[100:103], v226, s[20:21] offset:320
	global_load_dwordx2 v[104:105], v227, s[22:23] offset:0
	global_load_dwordx2 v[106:107], v227, s[22:23] offset:32
	global_load_dwordx2 v[108:109], v228, s[22:23] offset:0
	global_load_dwordx2 v[110:111], v228, s[22:23] offset:32
	global_load_dwordx2 v[112:113], v227, s[24:25] offset:0
	global_load_dwordx2 v[114:115], v227, s[24:25] offset:32
	global_load_dwordx2 v[120:121], v229, s[42:43]
	s_and_b32 s17, s10, s32
	s_xor_b32 s17, s17, s32
	s_cmp_eq_u32 s17, 0
	s_cbranch_scc1 .Lrw0_hnrw47
	global_load_dwordx2 v[116:117], v228, s[24:25] offset:0
	global_load_dwordx2 v[118:119], v228, s[24:25] offset:32
.Lrw0_hnrw47:
.Lrw0_b2:
	s_barrier
	s_cmp_lt_u32 s10, 68
	s_cbranch_scc1 .Lrw0_chunk
	v_mov_b32_e32 v1, s34
	v_mov_b32_e32 v2, s35

;     __device__ __forceinline__ bf16* R(int i) const { return (bf16*)(ws + OFF_R0 + (size_t)i * RSZ); }
; __device__ __forceinline__ void phase_rwkv_scan(const Fr& F, int jr) {
;     ...
;     const int bxs = (int)blockIdx.x, bxcd = (gridDim.x == 256) ? (bxs & 7) * 32 + (bxs >> 3) : bxs;
;     for (int task = bxcd; task < 256; task += gridDim.x) {
;         const int half = task & 1, h = (task >> 1) & 15, b = (task >> 5) & 3, s = task >> 7;
;         bf16* Yb = F.R(s);
;         const float* w0 = F.a->in[9] + (size_t)(jr * 2 + s) * D + h * 64; const float* a0 = F.a->in[12] + (size_t)(jr * 2 + s) * D + h * 64;
;         const float* kkw = F.a->in[15] + (size_t)jr * D + h * 64; const float* kaw = F.a->in[16] + (size_t)jr * D + h * 64;
;         f32x2 S01 = {0.f, 0.f}, S23 = {0.f, 0.f};
;         const int ks = 4 * l15, rloc = 4 * wave + lq;
;     ...
;                 float* Ypw = Yp + wave * 1024;
;                 unsigned a1 = (unsigned)(size_t)(__attribute__((address_space(3))) float*)(Wv + ks), a2 = (unsigned)(size_t)(__attribute__((address_space(3))) float*)(Rr + ks),
;                          a3 = (unsigned)(size_t)(__attribute__((address_space(3))) float*)(Vv + rloc), a4 = (unsigned)(size_t)(__attribute__((address_space(3))) float*)(Ypw + lane);
;                 asm volatile("" : "+v"(a1), "+v"(a2), "+v"(a3), "+v"(a4));
;                 typedef const __attribute__((address_space(3))) f32x4* lp4; typedef const __attribute__((address_space(3))) float* lp1; typedef __attribute__((address_space(3))) float* lw1;
;                 const lp4 PW = (lp4)a1, PR = (lp4)a2; const lp1 PV = (lp1)a3; const lw1 PY = (lw1)a4;
.LBB0_2530:
	s_cmp_lt_i32 s34, 26
	s_cselect_b64 s[6:7], -1, 0
	s_cmp_gt_i32 s35, 25
	s_cselect_b64 s[8:9], -1, 0
	s_and_b64 s[6:7], s[6:7], s[8:9]
	s_andn2_b64 vcc, exec, s[6:7]
	s_cbranch_vccnz .LBB0_2542
	s_and_b32 s3, s2, 7
	s_lshl_b32 s3, s3, 5
	s_lshr_b32 s6, s2, 3
	s_add_i32 s3, s3, s6
	s_lshr_b32 s6, s3, 7
	s_bfe_u32 s7, s3, 0x20005
	s_bfe_u32 s8, s3, 0x40001
	s_and_b32 s9, s3, 1
	s_cmp_gt_u32 s68, 3
	s_cbranch_scc1 .Lrw3_nosc
	v_mov_b32_e32 v236, 0
	v_mov_b32_e32 v237, 0
	v_mov_b32_e32 v238, 0
	v_mov_b32_e32 v239, 0
	v_mov_b32_e32 v240, 0
	v_mov_b32_e32 v241, 0
	v_mov_b32_e32 v242, 0
	v_mov_b32_e32 v243, 0
	v_and_b32_e32 v197, 15, v130
	v_lshlrev_b32_e32 v244, 4, v197
	v_add_u32_e32 v245, 0x11000, v244
	v_lshrrev_b32_e32 v198, 4, v130
	v_lshrrev_b32_e32 v199, 3, v197
	v_lshl_add_u32 v199, v198, 1, v199
	s_lshl_b32 s91, s68, 3
	v_add_u32_e32 v199, s91, v199
	v_lshlrev_b32_e32 v199, 3, v199
	v_add_u32_e32 v246, 0x15400, v199
	s_mul_i32 s91, s68, 0x2400
	s_add_i32 s91, s91, 0x19800
	s_cmp_eq_u32 s68, 3
	s_cselect_b32 s91, 0x20800, s91
	v_mul_u32_u24_e32 v248, 0x90, v130
	v_add_u32_e32 v248, s91, v248
	v_mul_u32_u24_e32 v198, 0x90, v198
	v_lshl_add_u32 v198, v197, 3, v198
	v_add_u32_e32 v247, s91, v198
	v_lshrrev_b32_e32 v249, 2, v130
	s_cmp_eq_u32 s6, 0
	s_cbranch_scc1 .Lrw3_sdir0
	v_sub_u32_e32 v249, 0, v249

;     __device__ __forceinline__ bf16* R(int i) const { return (bf16*)(ws + OFF_R0 + (size_t)i * RSZ); }
; __device__ __forceinline__ void phase_rwkv_scan(const Fr& F, int jr) {
;     ...
;     const int bxs = (int)blockIdx.x, bxcd = (gridDim.x == 256) ? (bxs & 7) * 32 + (bxs >> 3) : bxs;
;     for (int task = bxcd; task < 256; task += gridDim.x) {
;         const int half = task & 1, h = (task >> 1) & 15, b = (task >> 5) & 3, s = task >> 7;
;         bf16* Yb = F.R(s);
;         const float* w0 = F.a->in[9] + (size_t)(jr * 2 + s) * D + h * 64; const float* a0 = F.a->in[12] + (size_t)(jr * 2 + s) * D + h * 64;
;         const float* kkw = F.a->in[15] + (size_t)jr * D + h * 64; const float* kaw = F.a->in[16] + (size_t)jr * D + h * 64;
;         f32x2 S01 = {0.f, 0.f}, S23 = {0.f, 0.f};
;         const int ks = 4 * l15, rloc = 4 * wave + lq;
;         const int pt = wave & 3, ht0 = (wave >> 2) * 2;
;         const int p1 = pt * 16 + l15;
;         const int p2 = tid >> 3, j8 = tid & 7, hk0 = 8 * j8;
;         bf16x8 Bw[2][2], Ba[2][2]; float w0v[2], a0v[2];
; #pragma unroll
;         for (int hh = 0; hh < 2; ++hh) { const int hk = (ht0 + hh) * 16 + l15, e = h * 64 + hk; w0v[hh] = w0[hk]; a0v[hh] = a0[hk];
; #pragma unroll
;             for (int kst = 0; kst < 2; ++kst) { Bw[hh][kst] = *(const bf16x8*)(L2T + ((size_t)s * D + e) * 64 + 32 * kst + 8 * lq); Ba[hh][kst] = *(const bf16x8*)(L2T + ((size_t)(2 + s) * D + e) * 64 + 32 * kst + 8 * lq); } }
;         float kkc[8], kac[8], rkc[8];
; #pragma unroll
;         for (int i = 0; i < 8; ++i) { kkc[i] = kkw[hk0 + i]; kac[i] = kaw[hk0 + i]; rkc[i] = F.a->in[17][(size_t)jr * D + h * 64 + hk0 + i]; }
;         float* Bon = (float*)(F.ws + OFF_R0 + 6 * RSZ + 16 * MiB);
;         bf16x8 Aw[2], Aa[2]; u32x4 kw, rw; u32x2 vw;
;         {   const size_t row1 = (size_t)b * TB + tokof(s, p1), row2 = (size_t)b * TB + tokof(s, p2);
; #pragma unroll
;             for (int kst = 0; kst < 2; ++kst) { Aw[kst] = *(const bf16x8*)(LM + row1 * 256 + 64 * s + 32 * kst + 8 * lq); Aa[kst] = *(const bf16x8*)(LM + row1 * 256 + 128 + 64 * s + 32 * kst + 8 * lq); }
;             kw = *(const u32x4*)(Kb + row2 * D + h * 64 + hk0); rw = *(const u32x4*)(Rb + row2 * D + h * 64 + hk0); vw = *(const u32x2*)(Vb + row2 * D + h * 64 + 32 * half + 4 * j8); }
.Lrw3_hdir0:
	s_mul_i32 s16, s7, 0x1100
	v_lshlrev_b32_e32 v221, 4, v217
	s_lshl_b32 s17, s15, 6
	v_lshl_add_u32 v219, v217, 3, s17
	s_xor_b32 s18, s17, 64
	v_lshl_add_u32 v220, v217, 3, s18
	s_lshl_b32 s17, s15, 7
	v_mul_u32_u24_e32 v197, 0x110, v216
	v_add_u32_e32 v197, s17, v197
	v_lshl_add_u32 v222, v217, 4, v197
	v_add_u32_e32 v224, 0x11000, v222
	v_lshl_add_u32 v223, v217, 5, v197
	v_add_u32_e32 v223, 0x15400, v223
	s_lshl_b32 s17, s6, 7
	s_add_u32 s20, s26, 0xde00000
	s_addc_u32 s21, s27, 0
	s_add_u32 s20, s20, s17
	s_addc_u32 s21, s21, 0
	s_lshl_b32 s17, s8, 7
	s_add_u32 s22, s26, 0xbc00000
	s_addc_u32 s23, s27, 0
	s_add_u32 s22, s22, s17
	s_addc_u32 s23, s23, 0
	s_add_u32 s24, s26, 0x9a00000
	s_addc_u32 s25, s27, 0
	s_add_u32 s24, s24, s17
	s_addc_u32 s25, s25, 0
	s_lshl_b32 s18, s9, 6
	s_add_i32 s17, s17, s18
	s_lshl_b32 s18, s15, 5
	s_add_i32 s17, s17, s18
	s_add_u32 s42, s26, 0x5600000
	s_addc_u32 s43, s27, 0
	s_add_u32 s42, s42, s17
	s_addc_u32 s43, s43, 0
	s_lshl_b32 s17, s8, 2
	s_add_u32 s44, s26, 0xee00000
	s_addc_u32 s45, s27, 0
	s_add_u32 s44, s44, s17
	s_addc_u32 s45, s45, 0
	s_or_b32 s17, s9, s15
	s_cmp_eq_u32 s17, 0
	s_cselect_b32 s32, 1, 0
	s_load_dwordx2 s[46:47], s[0:1], 0x48
	s_load_dwordx2 s[48:49], s[0:1], 0x60
	s_load_dwordx2 s[50:51], s[0:1], 0x78
	s_load_dwordx2 s[52:53], s[0:1], 0x80
	s_load_dwordx2 s[54:55], s[0:1], 0x88
	s_lshl_b32 s17, s8, 8
	s_lshl_b32 s18, s15, 7
	s_add_i32 s19, s17, s18
	v_lshl_add_u32 v198, v217, 4, s19
	s_xor_b32 s18, s18, 128
	s_add_i32 s19, s17, s18
	v_lshl_add_u32 v199, v217, 4, s19
	s_waitcnt lgkmcnt(0)
	s_lshl_b32 s17, s6, 12
	s_add_u32 s46, s46, s17
	s_addc_u32 s47, s47, 0
	s_add_u32 s48, s48, s17
	s_addc_u32 s49, s49, 0
	s_add_u32 s46, s46, 0x2000
	s_addc_u32 s47, s47, 0
	s_add_u32 s48, s48, 0x2000
	s_addc_u32 s49, s49, 0
	s_add_u32 s50, s50, 0x1000
	s_addc_u32 s51, s51, 0
	s_add_u32 s52, s52, 0x1000
	s_addc_u32 s53, s53, 0
	s_add_u32 s54, s54, 0x1000
	s_addc_u32 s55, s55, 0
	global_load_dwordx4 v[32:35], v198, s[46:47] offset:0
	global_load_dwordx4 v[40:43], v198, s[48:49] offset:0
	global_load_dwordx4 v[64:67], v198, s[52:53] offset:0
	global_load_dwordx4 v[36:39], v198, s[46:47] offset:64
	global_load_dwordx4 v[44:47], v198, s[48:49] offset:64
	global_load_dwordx4 v[68:71], v198, s[52:53] offset:64
	global_load_dwordx4 v[48:51], v198, s[50:51] offset:0
	global_load_dwordx4 v[72:75], v198, s[54:55] offset:0
	global_load_dwordx4 v[52:55], v198, s[50:51] offset:64
	global_load_dwordx4 v[76:79], v198, s[54:55] offset:64
	global_load_dwordx4 v[56:59], v199, s[50:51] offset:0
	global_load_dwordx4 v[80:83], v199, s[54:55] offset:0
	global_load_dwordx4 v[60:63], v199, s[50:51] offset:64
	global_load_dwordx4 v[84:87], v199, s[54:55] offset:64
	s_lshl_b32 s17, s8, 6
	s_lshl_b32 s18, s15, 5
	s_add_i32 s17, s17, s18
	v_add_u32_e32 v200, s17, v196
	v_lshlrev_b32_e32 v200, 7, v200
	v_add_u32_e32 v200, v200, v221
	s_lshl_b32 s17, s6, 17
	s_add_u32 s46, s26, 0x200000
	s_addc_u32 s47, s27, 0
	s_add_u32 s46, s46, s17
	s_addc_u32 s47, s47, 0
	s_add_u32 s48, s46, 0x40000
	s_addc_u32 s49, s47, 0
	global_load_dwordx4 v[0:3], v200, s[46:47] offset:0
	global_load_dwordx4 v[16:19], v200, s[48:49] offset:0
	global_load_dwordx4 v[4:7], v200, s[46:47] offset:64
	global_load_dwordx4 v[20:23], v200, s[48:49] offset:64
	global_load_dwordx4 v[8:11], v200, s[46:47] offset:2048
	global_load_dwordx4 v[24:27], v200, s[48:49] offset:2048
	global_load_dwordx4 v[12:15], v200, s[46:47] offset:2112
	global_load_dwordx4 v[28:31], v200, s[48:49] offset:2112
	s_mov_b32 s10, 0
	s_lshl_b32 s17, s10, 6
	s_cmp_lt_u32 s10, 4
	s_movk_i32 s18, 0x11ff
	s_cselect_b32 s18, 0xff, s18
	s_sub_i32 s18, s18, s17
	s_cmp_eq_u32 s6, 0
	s_cselect_b32 s17, s17, s18
	s_add_i32 s17, s17, s16
	v_add_u32_e32 v231, s17, v218
	v_lshl_add_u32 v226, v231, 9, v221
	v_lshl_add_u32 v227, v231, 11, v219
	v_lshl_add_u32 v228, v231, 11, v220
	v_lshlrev_b32_e32 v229, 3, v217
	v_lshl_add_u32 v229, v231, 11, v229
	v_lshlrev_b32_e32 v230, 6, v231
	global_load_dwordx4 v[88:91], v226, s[20:21]
	global_load_dwordx4 v[92:95], v226, s[20:21] offset:64
	global_load_dwordx4 v[96:99], v226, s[20:21] offset:256
	global_load_dwordx4 v[100:103], v226, s[20:21] offset:320
	global_load_dwordx2 v[104:105], v227, s[22:23] offset:0
	global_load_dwordx2 v[106:107], v227, s[22:23] offset:32
	global_load_dwordx2 v[108:109], v228, s[22:23] offset:0
	global_load_dwordx2 v[110:111], v228, s[22:23] offset:32
	global_load_dwordx2 v[112:113], v227, s[24:25] offset:0
	global_load_dwordx2 v[114:115], v227, s[24:25] offset:32
	global_load_dwordx2 v[116:117], v228, s[24:25] offset:0
	global_load_dwordx2 v[118:119], v228, s[24:25] offset:32
	global_load_dwordx2 v[120:121], v229, s[42:43]

; #define LDS_BAR() asm volatile("s_waitcnt lgkmcnt(0)\n\ts_barrier" ::: "memory")
; __device__ __forceinline__ void phase_rwkv_scan(const Fr& F, int jr) {
;     ...
;             LDS_BAR();
;         }
;         LDS_BAR();
.Lrw3_hnrw47:
.Lrw3_b2:
	s_barrier
	s_cmp_lt_u32 s10, 68
	s_cbranch_scc1 .Lrw3_chunk
